# SwiGLU activation stores without the nt hint (stay in L2/MALL for the w2 GEMM that reads them next)
# speedup vs baseline: 1.0157x; 1.0115x over previous
.LBB0_114:
	v_lshl_add_u32 v144, s6, 8, v147
	v_ashrrev_i32_e32 v145, 31, v144
	v_lshl_add_u64 v[162:163], v[144:145], 2, s[8:9]
	global_load_dword v145, v[162:163], off
	global_load_dword v146, v[162:163], off offset:64
	global_load_dword v149, v[162:163], off offset:128
	global_load_dword v150, v[162:163], off offset:192
	global_load_dword v152, v[162:163], off offset:512
	global_load_dword v164, v[162:163], off offset:576
	global_load_dword v165, v[162:163], off offset:640
	s_nop 0
	global_load_dword v163, v[162:163], off offset:704
	v_lshl_or_b32 v148, s7, 7, v153
	s_andn2_b64 vcc, exec, s[4:5]
	s_waitcnt vmcnt(0)
	v_fmamk_f32 v145, v145, 0x3a800000, v161
	v_rsq_f32_e32 v162, v145
	v_fmamk_f32 v145, v146, 0x3a800000, v161
	v_rsq_f32_e32 v160, v145
	v_fmamk_f32 v145, v149, 0x3a800000, v161
	v_rsq_f32_e32 v158, v145
	v_fmamk_f32 v145, v150, 0x3a800000, v161
	v_rsq_f32_e32 v156, v145
	v_fmamk_f32 v145, v152, 0x3a800000, v161
	v_rsq_f32_e32 v154, v145
	v_fmamk_f32 v145, v164, 0x3a800000, v161
	v_rsq_f32_e32 v152, v145
	v_fmamk_f32 v145, v165, 0x3a800000, v161
	v_rsq_f32_e32 v150, v145
	v_fmamk_f32 v145, v163, 0x3a800000, v161
	v_pk_mul_f32 v[124:125], v[124:125], v[162:163] op_sel_hi:[1,0]
	v_rsq_f32_e32 v146, v145
	v_mul_f32_e32 v145, 0xbfb8aa3b, v124
	v_exp_f32_e32 v145, v145
	v_pk_mul_f32 v[116:117], v[116:117], v[162:163] op_sel_hi:[1,0]
	v_pk_mul_f32 v[118:119], v[118:119], v[162:163] op_sel_hi:[1,0]
	v_pk_mul_f32 v[120:121], v[120:121], v[162:163] op_sel_hi:[1,0]
	v_add_f32_e32 v145, 1.0, v145
	v_rcp_f32_e32 v164, v145
	v_mul_f32_e32 v145, 0xbfb8aa3b, v125
	v_exp_f32_e32 v145, v145
	v_pk_mul_f32 v[112:113], v[112:113], v[162:163] op_sel_hi:[1,0]
	v_ashrrev_i32_e32 v149, 31, v148
	v_pk_mul_f32 v[114:115], v[114:115], v[162:163] op_sel_hi:[1,0]
	v_add_f32_e32 v145, 1.0, v145
	v_rcp_f32_e32 v165, v145
	v_lshl_add_u64 v[148:149], v[148:149], 1, s[68:69]
	v_pk_mul_f32 v[108:109], v[108:109], v[160:161] op_sel_hi:[1,0]
	v_pk_mul_f32 v[104:105], v[104:105], v[160:161] op_sel_hi:[1,0]
	v_pk_mul_f32 v[124:125], v[124:125], v[164:165]
	v_pk_mul_f32 v[106:107], v[106:107], v[160:161] op_sel_hi:[1,0]
	v_pk_mul_f32 v[116:117], v[116:117], v[124:125]
	v_pk_mul_f32 v[124:125], v[126:127], v[162:163] op_sel_hi:[1,0]
	v_pk_mul_f32 v[100:101], v[100:101], v[160:161] op_sel_hi:[1,0]
	v_mul_f32_e32 v126, 0xbfb8aa3b, v124
	v_mul_f32_e32 v127, 0xbfb8aa3b, v125
	v_exp_f32_e32 v126, v126
	v_exp_f32_e32 v127, v127
	v_pk_mul_f32 v[96:97], v[96:97], v[160:161] op_sel_hi:[1,0]
	v_pk_mul_f32 v[98:99], v[98:99], v[160:161] op_sel_hi:[1,0]
	v_add_f32_e32 v126, 1.0, v126
	v_add_f32_e32 v127, 1.0, v127
	v_rcp_f32_e32 v126, v126
	v_rcp_f32_e32 v127, v127
	v_pk_mul_f32 v[92:93], v[92:93], v[158:159] op_sel_hi:[1,0]
	v_pk_mul_f32 v[88:89], v[88:89], v[158:159] op_sel_hi:[1,0]
	v_pk_mul_f32 v[90:91], v[90:91], v[158:159] op_sel_hi:[1,0]
	v_pk_mul_f32 v[124:125], v[124:125], v[126:127]
	v_pk_mul_f32 v[84:85], v[84:85], v[158:159] op_sel_hi:[1,0]
	v_pk_mul_f32 v[118:119], v[118:119], v[124:125]
	v_mul_f32_e32 v124, 0xbfb8aa3b, v120
	v_mul_f32_e32 v125, 0xbfb8aa3b, v121
	v_exp_f32_e32 v124, v124
	v_exp_f32_e32 v125, v125
	v_pk_mul_f32 v[80:81], v[80:81], v[158:159] op_sel_hi:[1,0]
	v_pk_mul_f32 v[82:83], v[82:83], v[158:159] op_sel_hi:[1,0]
	v_add_f32_e32 v124, 1.0, v124
	v_add_f32_e32 v125, 1.0, v125
	v_rcp_f32_e32 v124, v124
	v_rcp_f32_e32 v125, v125
	v_pk_mul_f32 v[76:77], v[76:77], v[156:157] op_sel_hi:[1,0]
	v_pk_mul_f32 v[72:73], v[72:73], v[156:157] op_sel_hi:[1,0]
	v_pk_mul_f32 v[74:75], v[74:75], v[156:157] op_sel_hi:[1,0]
	v_pk_mul_f32 v[120:121], v[120:121], v[124:125]
	v_pk_mul_f32 v[68:69], v[68:69], v[156:157] op_sel_hi:[1,0]
	v_pk_mul_f32 v[120:121], v[112:113], v[120:121]
	v_pk_mul_f32 v[112:113], v[122:123], v[162:163] op_sel_hi:[1,0]
	v_pk_mul_f32 v[64:65], v[64:65], v[156:157] op_sel_hi:[1,0]
	v_mul_f32_e32 v122, 0xbfb8aa3b, v112
	v_mul_f32_e32 v123, 0xbfb8aa3b, v113
	v_exp_f32_e32 v122, v122
	v_exp_f32_e32 v123, v123
	v_pk_mul_f32 v[66:67], v[66:67], v[156:157] op_sel_hi:[1,0]
	v_pk_mul_f32 v[60:61], v[60:61], v[154:155] op_sel_hi:[1,0]
	v_add_f32_e32 v122, 1.0, v122
	v_add_f32_e32 v123, 1.0, v123
	v_rcp_f32_e32 v122, v122
	v_rcp_f32_e32 v123, v123
	v_pk_mul_f32 v[56:57], v[56:57], v[154:155] op_sel_hi:[1,0]
	v_pk_mul_f32 v[58:59], v[58:59], v[154:155] op_sel_hi:[1,0]
	v_pk_mul_f32 v[52:53], v[52:53], v[154:155] op_sel_hi:[1,0]
	v_pk_mul_f32 v[112:113], v[112:113], v[122:123]
	v_pk_mul_f32 v[48:49], v[48:49], v[154:155] op_sel_hi:[1,0]
	v_pk_mul_f32 v[122:123], v[114:115], v[112:113]
	v_cvt_pk_bf16_f32 v112, v116, v117
	v_cvt_pk_bf16_f32 v113, v118, v119
	v_cvt_pk_bf16_f32 v114, v120, v121
	v_cvt_pk_bf16_f32 v115, v122, v123
	v_mad_i64_i32 v[116:117], s[6:7], v144, s75, v[148:149]
	global_store_dwordx4 v[116:117], v[112:115], off
	v_pk_mul_f32 v[50:51], v[50:51], v[154:155] op_sel_hi:[1,0]
	v_pk_mul_f32 v[44:45], v[44:45], v[152:153] op_sel_hi:[1,0]
	v_mul_f32_e32 v112, 0xbfb8aa3b, v108
	v_mul_f32_e32 v113, 0xbfb8aa3b, v109
	v_exp_f32_e32 v112, v112
	v_exp_f32_e32 v113, v113
	v_pk_mul_f32 v[40:41], v[40:41], v[152:153] op_sel_hi:[1,0]
	v_pk_mul_f32 v[42:43], v[42:43], v[152:153] op_sel_hi:[1,0]
	v_add_f32_e32 v112, 1.0, v112
	v_add_f32_e32 v113, 1.0, v113
	v_rcp_f32_e32 v112, v112
	v_rcp_f32_e32 v113, v113
	v_pk_mul_f32 v[36:37], v[36:37], v[152:153] op_sel_hi:[1,0]
	v_pk_mul_f32 v[32:33], v[32:33], v[152:153] op_sel_hi:[1,0]
	v_pk_mul_f32 v[34:35], v[34:35], v[152:153] op_sel_hi:[1,0]
	v_pk_mul_f32 v[108:109], v[108:109], v[112:113]
	v_pk_mul_f32 v[28:29], v[28:29], v[150:151] op_sel_hi:[1,0]
	v_pk_mul_f32 v[104:105], v[104:105], v[108:109]
	v_pk_mul_f32 v[108:109], v[110:111], v[160:161] op_sel_hi:[1,0]
	v_pk_mul_f32 v[24:25], v[24:25], v[150:151] op_sel_hi:[1,0]
	v_mul_f32_e32 v110, 0xbfb8aa3b, v108
	v_mul_f32_e32 v111, 0xbfb8aa3b, v109
	v_exp_f32_e32 v110, v110
	v_exp_f32_e32 v111, v111
	v_pk_mul_f32 v[26:27], v[26:27], v[150:151] op_sel_hi:[1,0]
	v_pk_mul_f32 v[20:21], v[20:21], v[150:151] op_sel_hi:[1,0]
	v_add_f32_e32 v110, 1.0, v110
	v_add_f32_e32 v111, 1.0, v111
	v_rcp_f32_e32 v110, v110
	v_rcp_f32_e32 v111, v111
	v_pk_mul_f32 v[16:17], v[16:17], v[150:151] op_sel_hi:[1,0]
	v_pk_mul_f32 v[18:19], v[18:19], v[150:151] op_sel_hi:[1,0]
	v_pk_mul_f32 v[12:13], v[12:13], v[146:147] op_sel_hi:[1,0]
	v_pk_mul_f32 v[108:109], v[108:109], v[110:111]
	v_pk_mul_f32 v[8:9], v[8:9], v[146:147] op_sel_hi:[1,0]
	v_pk_mul_f32 v[106:107], v[106:107], v[108:109]
	v_mul_f32_e32 v108, 0xbfb8aa3b, v100
	v_mul_f32_e32 v109, 0xbfb8aa3b, v101
	v_exp_f32_e32 v108, v108
	v_exp_f32_e32 v109, v109
	v_pk_mul_f32 v[10:11], v[10:11], v[146:147] op_sel_hi:[1,0]
	v_pk_mul_f32 v[4:5], v[4:5], v[146:147] op_sel_hi:[1,0]
	v_add_f32_e32 v108, 1.0, v108
	v_add_f32_e32 v109, 1.0, v109
	v_rcp_f32_e32 v108, v108
	v_rcp_f32_e32 v109, v109
	v_pk_mul_f32 v[0:1], v[0:1], v[146:147] op_sel_hi:[1,0]
	v_pk_mul_f32 v[2:3], v[2:3], v[146:147] op_sel_hi:[1,0]
	v_pk_mul_f32 v[100:101], v[100:101], v[108:109]
	s_nop 0
	v_pk_mul_f32 v[100:101], v[96:97], v[100:101]
	v_pk_mul_f32 v[96:97], v[102:103], v[160:161] op_sel_hi:[1,0]
	v_or_b32_e32 v108, 16, v144
	v_mul_f32_e32 v102, 0xbfb8aa3b, v96
	v_mul_f32_e32 v103, 0xbfb8aa3b, v97
	v_exp_f32_e32 v102, v102
	v_exp_f32_e32 v103, v103
	v_add_f32_e32 v102, 1.0, v102
	v_add_f32_e32 v103, 1.0, v103
	v_rcp_f32_e32 v102, v102
	v_rcp_f32_e32 v103, v103
	s_nop 0
	v_pk_mul_f32 v[96:97], v[96:97], v[102:103]
	s_nop 0
	v_pk_mul_f32 v[102:103], v[98:99], v[96:97]
	v_cvt_pk_bf16_f32 v96, v104, v105
	v_cvt_pk_bf16_f32 v97, v106, v107
	v_cvt_pk_bf16_f32 v98, v100, v101
	v_cvt_pk_bf16_f32 v99, v102, v103
	v_mad_i64_i32 v[100:101], s[6:7], v108, s75, v[148:149]
	global_store_dwordx4 v[100:101], v[96:99], off
	s_nop 1
	v_mul_f32_e32 v96, 0xbfb8aa3b, v92
	v_mul_f32_e32 v97, 0xbfb8aa3b, v93
	v_exp_f32_e32 v96, v96
	v_exp_f32_e32 v97, v97
	v_add_f32_e32 v96, 1.0, v96
	v_add_f32_e32 v97, 1.0, v97
	v_rcp_f32_e32 v96, v96
	v_rcp_f32_e32 v97, v97
	s_nop 0
	v_pk_mul_f32 v[92:93], v[92:93], v[96:97]
	s_nop 0
	v_pk_mul_f32 v[88:89], v[88:89], v[92:93]
	v_pk_mul_f32 v[92:93], v[94:95], v[158:159] op_sel_hi:[1,0]
	s_nop 0
	v_mul_f32_e32 v94, 0xbfb8aa3b, v92
	v_mul_f32_e32 v95, 0xbfb8aa3b, v93
	v_exp_f32_e32 v94, v94
	v_exp_f32_e32 v95, v95
	v_add_f32_e32 v94, 1.0, v94
	v_add_f32_e32 v95, 1.0, v95
	v_rcp_f32_e32 v94, v94
	v_rcp_f32_e32 v95, v95
	s_nop 0
	v_pk_mul_f32 v[92:93], v[92:93], v[94:95]
	s_nop 0
	v_pk_mul_f32 v[90:91], v[90:91], v[92:93]
	v_mul_f32_e32 v92, 0xbfb8aa3b, v84
	v_mul_f32_e32 v93, 0xbfb8aa3b, v85
	v_exp_f32_e32 v92, v92
	v_exp_f32_e32 v93, v93
	v_add_f32_e32 v92, 1.0, v92
	v_add_f32_e32 v93, 1.0, v93
	v_rcp_f32_e32 v92, v92
	v_rcp_f32_e32 v93, v93
	s_nop 0
	v_pk_mul_f32 v[84:85], v[84:85], v[92:93]
	s_nop 0
	v_pk_mul_f32 v[84:85], v[80:81], v[84:85]
	v_pk_mul_f32 v[80:81], v[86:87], v[158:159] op_sel_hi:[1,0]
	v_or_b32_e32 v92, 32, v144
	v_mul_f32_e32 v86, 0xbfb8aa3b, v80
	v_mul_f32_e32 v87, 0xbfb8aa3b, v81
	v_exp_f32_e32 v86, v86
	v_exp_f32_e32 v87, v87
	v_add_f32_e32 v86, 1.0, v86
	v_add_f32_e32 v87, 1.0, v87
	v_rcp_f32_e32 v86, v86
	v_rcp_f32_e32 v87, v87
	s_nop 0
	v_pk_mul_f32 v[80:81], v[80:81], v[86:87]
	s_nop 0
	v_pk_mul_f32 v[86:87], v[82:83], v[80:81]
	v_cvt_pk_bf16_f32 v80, v88, v89
	v_cvt_pk_bf16_f32 v81, v90, v91
	v_cvt_pk_bf16_f32 v82, v84, v85
	v_cvt_pk_bf16_f32 v83, v86, v87
	v_mad_i64_i32 v[84:85], s[6:7], v92, s75, v[148:149]
	global_store_dwordx4 v[84:85], v[80:83], off
	s_nop 1
	v_mul_f32_e32 v80, 0xbfb8aa3b, v76
	v_mul_f32_e32 v81, 0xbfb8aa3b, v77
	v_exp_f32_e32 v80, v80
	v_exp_f32_e32 v81, v81
	v_add_f32_e32 v80, 1.0, v80
	v_add_f32_e32 v81, 1.0, v81
	v_rcp_f32_e32 v80, v80
	v_rcp_f32_e32 v81, v81
	s_nop 0
	v_pk_mul_f32 v[76:77], v[76:77], v[80:81]
	s_nop 0
	v_pk_mul_f32 v[72:73], v[72:73], v[76:77]
	v_pk_mul_f32 v[76:77], v[78:79], v[156:157] op_sel_hi:[1,0]
	s_nop 0
	v_mul_f32_e32 v78, 0xbfb8aa3b, v76
	v_mul_f32_e32 v79, 0xbfb8aa3b, v77
	v_exp_f32_e32 v78, v78
	v_exp_f32_e32 v79, v79
	v_add_f32_e32 v78, 1.0, v78
	v_add_f32_e32 v79, 1.0, v79
	v_rcp_f32_e32 v78, v78
	v_rcp_f32_e32 v79, v79
	s_nop 0
	v_pk_mul_f32 v[76:77], v[76:77], v[78:79]
	s_nop 0
	v_pk_mul_f32 v[74:75], v[74:75], v[76:77]
	v_mul_f32_e32 v76, 0xbfb8aa3b, v68
	v_mul_f32_e32 v77, 0xbfb8aa3b, v69
	v_exp_f32_e32 v76, v76
	v_exp_f32_e32 v77, v77
	v_add_f32_e32 v76, 1.0, v76
	v_add_f32_e32 v77, 1.0, v77
	v_rcp_f32_e32 v76, v76
	v_rcp_f32_e32 v77, v77
	s_nop 0
	v_pk_mul_f32 v[68:69], v[68:69], v[76:77]
	s_nop 0
	v_pk_mul_f32 v[68:69], v[64:65], v[68:69]
	v_pk_mul_f32 v[64:65], v[70:71], v[156:157] op_sel_hi:[1,0]
	v_or_b32_e32 v76, 48, v144
	v_mul_f32_e32 v70, 0xbfb8aa3b, v64
	v_mul_f32_e32 v71, 0xbfb8aa3b, v65
	v_exp_f32_e32 v70, v70
	v_exp_f32_e32 v71, v71
	v_add_f32_e32 v70, 1.0, v70
	v_add_f32_e32 v71, 1.0, v71
	v_rcp_f32_e32 v70, v70
	v_rcp_f32_e32 v71, v71
	s_nop 0
	v_pk_mul_f32 v[64:65], v[64:65], v[70:71]
	s_nop 0
	v_pk_mul_f32 v[70:71], v[66:67], v[64:65]
	v_cvt_pk_bf16_f32 v64, v72, v73
	v_cvt_pk_bf16_f32 v65, v74, v75
	v_cvt_pk_bf16_f32 v66, v68, v69
	v_cvt_pk_bf16_f32 v67, v70, v71
	v_mad_i64_i32 v[68:69], s[6:7], v76, s75, v[148:149]
	global_store_dwordx4 v[68:69], v[64:67], off
	s_nop 1
	v_mul_f32_e32 v64, 0xbfb8aa3b, v60
	v_mul_f32_e32 v65, 0xbfb8aa3b, v61
	v_exp_f32_e32 v64, v64
	v_exp_f32_e32 v65, v65
	v_add_u32_e32 v66, 0x80, v144
	v_add_f32_e32 v64, 1.0, v64
	v_add_f32_e32 v65, 1.0, v65
	v_rcp_f32_e32 v64, v64
	v_rcp_f32_e32 v65, v65
	s_nop 0
	v_pk_mul_f32 v[60:61], v[60:61], v[64:65]
	s_nop 0
	v_pk_mul_f32 v[56:57], v[56:57], v[60:61]
	v_pk_mul_f32 v[60:61], v[62:63], v[154:155] op_sel_hi:[1,0]
	s_nop 0
	v_mul_f32_e32 v62, 0xbfb8aa3b, v60
	v_mul_f32_e32 v63, 0xbfb8aa3b, v61
	v_exp_f32_e32 v62, v62
	v_exp_f32_e32 v63, v63
	v_add_f32_e32 v62, 1.0, v62
	v_add_f32_e32 v63, 1.0, v63
	v_rcp_f32_e32 v62, v62
	v_rcp_f32_e32 v63, v63
	s_nop 0
	v_pk_mul_f32 v[60:61], v[60:61], v[62:63]
	s_nop 0
	v_pk_mul_f32 v[58:59], v[58:59], v[60:61]
	v_mul_f32_e32 v60, 0xbfb8aa3b, v52
	v_mul_f32_e32 v61, 0xbfb8aa3b, v53
	v_exp_f32_e32 v60, v60
	v_exp_f32_e32 v61, v61
	v_add_f32_e32 v60, 1.0, v60
	v_add_f32_e32 v61, 1.0, v61
	v_rcp_f32_e32 v60, v60
	v_rcp_f32_e32 v61, v61
	s_nop 0
	v_pk_mul_f32 v[52:53], v[52:53], v[60:61]
	s_nop 0
	v_pk_mul_f32 v[52:53], v[48:49], v[52:53]
	v_pk_mul_f32 v[48:49], v[54:55], v[154:155] op_sel_hi:[1,0]
	s_nop 0
	v_mul_f32_e32 v54, 0xbfb8aa3b, v48
	v_mul_f32_e32 v55, 0xbfb8aa3b, v49
	v_exp_f32_e32 v54, v54
	v_exp_f32_e32 v55, v55
	v_add_f32_e32 v54, 1.0, v54
	v_add_f32_e32 v55, 1.0, v55
	v_rcp_f32_e32 v54, v54
	v_rcp_f32_e32 v55, v55
	s_nop 0
	v_pk_mul_f32 v[48:49], v[48:49], v[54:55]
	s_nop 0
	v_pk_mul_f32 v[54:55], v[50:51], v[48:49]
	v_cvt_pk_bf16_f32 v48, v56, v57
	v_cvt_pk_bf16_f32 v49, v58, v59
	v_cvt_pk_bf16_f32 v50, v52, v53
	v_cvt_pk_bf16_f32 v51, v54, v55
	v_mad_i64_i32 v[52:53], s[6:7], v66, s75, v[148:149]
	global_store_dwordx4 v[52:53], v[48:51], off
	s_nop 1
	v_mul_f32_e32 v48, 0xbfb8aa3b, v44
	v_mul_f32_e32 v49, 0xbfb8aa3b, v45
	v_exp_f32_e32 v48, v48
	v_exp_f32_e32 v49, v49
	v_add_f32_e32 v48, 1.0, v48
	v_add_f32_e32 v49, 1.0, v49
	v_rcp_f32_e32 v48, v48
	v_rcp_f32_e32 v49, v49
	s_nop 0
	v_pk_mul_f32 v[44:45], v[44:45], v[48:49]
	s_nop 0
	v_pk_mul_f32 v[40:41], v[40:41], v[44:45]
	v_pk_mul_f32 v[44:45], v[46:47], v[152:153] op_sel_hi:[1,0]
	s_nop 0
	v_mul_f32_e32 v46, 0xbfb8aa3b, v44
	v_mul_f32_e32 v47, 0xbfb8aa3b, v45
	v_exp_f32_e32 v46, v46
	v_exp_f32_e32 v47, v47
	v_add_f32_e32 v46, 1.0, v46
	v_add_f32_e32 v47, 1.0, v47
	v_rcp_f32_e32 v46, v46
	v_rcp_f32_e32 v47, v47
	s_nop 0
	v_pk_mul_f32 v[44:45], v[44:45], v[46:47]
	s_nop 0
	v_pk_mul_f32 v[42:43], v[42:43], v[44:45]
	v_mul_f32_e32 v44, 0xbfb8aa3b, v36
	v_mul_f32_e32 v45, 0xbfb8aa3b, v37
	v_exp_f32_e32 v44, v44
	v_exp_f32_e32 v45, v45
	v_add_f32_e32 v44, 1.0, v44
	v_add_f32_e32 v45, 1.0, v45
	v_rcp_f32_e32 v44, v44
	v_rcp_f32_e32 v45, v45
	s_nop 0
	v_pk_mul_f32 v[36:37], v[36:37], v[44:45]
	s_nop 0
	v_pk_mul_f32 v[36:37], v[32:33], v[36:37]
	v_pk_mul_f32 v[32:33], v[38:39], v[152:153] op_sel_hi:[1,0]
	v_add_u32_e32 v44, 0x90, v144
	v_mul_f32_e32 v38, 0xbfb8aa3b, v32
	v_mul_f32_e32 v39, 0xbfb8aa3b, v33
	v_exp_f32_e32 v38, v38
	v_exp_f32_e32 v39, v39
	v_add_f32_e32 v38, 1.0, v38
	v_add_f32_e32 v39, 1.0, v39
	v_rcp_f32_e32 v38, v38
	v_rcp_f32_e32 v39, v39
	s_nop 0
	v_pk_mul_f32 v[32:33], v[32:33], v[38:39]
	s_nop 0
	v_pk_mul_f32 v[38:39], v[34:35], v[32:33]
	v_cvt_pk_bf16_f32 v32, v40, v41
	v_cvt_pk_bf16_f32 v33, v42, v43
	v_cvt_pk_bf16_f32 v34, v36, v37
	v_cvt_pk_bf16_f32 v35, v38, v39
	v_mad_i64_i32 v[36:37], s[6:7], v44, s75, v[148:149]
	global_store_dwordx4 v[36:37], v[32:35], off
	s_nop 1
	v_mul_f32_e32 v32, 0xbfb8aa3b, v28
	v_mul_f32_e32 v33, 0xbfb8aa3b, v29
	v_exp_f32_e32 v32, v32
	v_exp_f32_e32 v33, v33
	v_add_f32_e32 v32, 1.0, v32
	v_add_f32_e32 v33, 1.0, v33
	v_rcp_f32_e32 v32, v32
	v_rcp_f32_e32 v33, v33
	s_nop 0
	v_pk_mul_f32 v[28:29], v[28:29], v[32:33]
	s_nop 0
	v_pk_mul_f32 v[24:25], v[24:25], v[28:29]
	v_pk_mul_f32 v[28:29], v[30:31], v[150:151] op_sel_hi:[1,0]
	s_nop 0
	v_mul_f32_e32 v30, 0xbfb8aa3b, v28
	v_mul_f32_e32 v31, 0xbfb8aa3b, v29
	v_exp_f32_e32 v30, v30
	v_exp_f32_e32 v31, v31
	v_add_f32_e32 v30, 1.0, v30
	v_add_f32_e32 v31, 1.0, v31
	v_rcp_f32_e32 v30, v30
	v_rcp_f32_e32 v31, v31
	s_nop 0
	v_pk_mul_f32 v[28:29], v[28:29], v[30:31]
	s_nop 0
	v_pk_mul_f32 v[26:27], v[26:27], v[28:29]
	v_mul_f32_e32 v28, 0xbfb8aa3b, v20
	v_mul_f32_e32 v29, 0xbfb8aa3b, v21
	v_exp_f32_e32 v28, v28
	v_exp_f32_e32 v29, v29
	v_add_f32_e32 v28, 1.0, v28
	v_add_f32_e32 v29, 1.0, v29
	v_rcp_f32_e32 v28, v28
	v_rcp_f32_e32 v29, v29
	s_nop 0
	v_pk_mul_f32 v[20:21], v[20:21], v[28:29]
	s_nop 0
	v_pk_mul_f32 v[20:21], v[16:17], v[20:21]
	v_pk_mul_f32 v[16:17], v[22:23], v[150:151] op_sel_hi:[1,0]
	v_add_u32_e32 v28, 0xa0, v144
	v_mul_f32_e32 v22, 0xbfb8aa3b, v16
	v_mul_f32_e32 v23, 0xbfb8aa3b, v17
	v_exp_f32_e32 v22, v22
	v_exp_f32_e32 v23, v23
	v_add_f32_e32 v22, 1.0, v22
	v_add_f32_e32 v23, 1.0, v23
	v_rcp_f32_e32 v22, v22
	v_rcp_f32_e32 v23, v23
	s_nop 0
	v_pk_mul_f32 v[16:17], v[16:17], v[22:23]
	s_nop 0
	v_pk_mul_f32 v[22:23], v[18:19], v[16:17]
	v_cvt_pk_bf16_f32 v16, v24, v25
	v_cvt_pk_bf16_f32 v17, v26, v27
	v_cvt_pk_bf16_f32 v18, v20, v21
	v_cvt_pk_bf16_f32 v19, v22, v23
	v_mad_i64_i32 v[20:21], s[6:7], v28, s75, v[148:149]
	global_store_dwordx4 v[20:21], v[16:19], off
	s_nop 1
	v_mul_f32_e32 v16, 0xbfb8aa3b, v12
	v_mul_f32_e32 v17, 0xbfb8aa3b, v13
	v_exp_f32_e32 v16, v16
	v_exp_f32_e32 v17, v17
	v_add_f32_e32 v16, 1.0, v16
	v_add_f32_e32 v17, 1.0, v17
	v_rcp_f32_e32 v16, v16
	v_rcp_f32_e32 v17, v17
	s_nop 0
	v_pk_mul_f32 v[12:13], v[12:13], v[16:17]
	s_nop 0
	v_pk_mul_f32 v[8:9], v[8:9], v[12:13]
	v_pk_mul_f32 v[12:13], v[14:15], v[146:147] op_sel_hi:[1,0]
	s_nop 0
	v_mul_f32_e32 v14, 0xbfb8aa3b, v12
	v_mul_f32_e32 v15, 0xbfb8aa3b, v13
	v_exp_f32_e32 v14, v14
	v_exp_f32_e32 v15, v15
	v_add_f32_e32 v14, 1.0, v14
	v_add_f32_e32 v15, 1.0, v15
	v_rcp_f32_e32 v14, v14
	v_rcp_f32_e32 v15, v15
	s_nop 0
	v_pk_mul_f32 v[12:13], v[12:13], v[14:15]
	s_nop 0
	v_pk_mul_f32 v[10:11], v[10:11], v[12:13]
	v_mul_f32_e32 v12, 0xbfb8aa3b, v4
	v_mul_f32_e32 v13, 0xbfb8aa3b, v5
	v_exp_f32_e32 v12, v12
	v_exp_f32_e32 v13, v13
	v_add_f32_e32 v12, 1.0, v12
	v_add_f32_e32 v13, 1.0, v13
	v_rcp_f32_e32 v12, v12
	v_rcp_f32_e32 v13, v13
	s_nop 0
	v_pk_mul_f32 v[4:5], v[4:5], v[12:13]
	s_nop 0
	v_pk_mul_f32 v[4:5], v[0:1], v[4:5]
	v_pk_mul_f32 v[0:1], v[6:7], v[146:147] op_sel_hi:[1,0]
	v_add_u32_e32 v12, 0xb0, v144
	v_mul_f32_e32 v6, 0xbfb8aa3b, v0
	v_mul_f32_e32 v7, 0xbfb8aa3b, v1
	v_exp_f32_e32 v6, v6
	v_exp_f32_e32 v7, v7
	v_add_f32_e32 v6, 1.0, v6
	v_add_f32_e32 v7, 1.0, v7
	v_rcp_f32_e32 v6, v6
	v_rcp_f32_e32 v7, v7
	s_nop 0
	v_pk_mul_f32 v[0:1], v[0:1], v[6:7]
	s_nop 0
	v_pk_mul_f32 v[6:7], v[2:3], v[0:1]
	v_cvt_pk_bf16_f32 v2, v4, v5
	v_mad_i64_i32 v[4:5], s[6:7], v12, s75, v[148:149]
	v_cvt_pk_bf16_f32 v0, v8, v9
	v_cvt_pk_bf16_f32 v1, v10, v11
	v_cvt_pk_bf16_f32 v3, v6, v7
	s_mov_b64 s[6:7], -1
	global_store_dwordx4 v[4:5], v[0:3], off
	s_cbranch_vccnz .LBB0_107
	s_andn2_b64 vcc, exec, s[10:11]
	s_cbranch_vccnz .LBB0_106
	s_barrier
	s_branch .LBB0_106

.LBB0_1118:
	v_lshl_add_u32 v144, s36, 8, v149
	v_ashrrev_i32_e32 v145, 31, v144
	v_lshl_add_u64 v[146:147], v[144:145], 2, s[10:11]
	global_load_dword v145, v[146:147], off
	global_load_dword v148, v[146:147], off offset:64
	global_load_dword v150, v[146:147], off offset:128
	global_load_dword v152, v[146:147], off offset:192
	global_load_dword v154, v[146:147], off offset:512
	global_load_dword v156, v[146:147], off offset:576
	global_load_dword v162, v[146:147], off offset:640
	global_load_dword v163, v[146:147], off offset:704
	v_lshl_or_b32 v146, s63, 7, v153
	v_ashrrev_i32_e32 v147, 31, v146
	v_lshl_add_u64 v[146:147], v[146:147], 1, s[68:69]
	v_mad_i64_i32 v[160:161], s[38:39], v144, s62, v[146:147]
	s_andn2_b64 vcc, exec, s[4:5]
	s_mov_b64 s[4:5], -1
	s_waitcnt vmcnt(0)
	v_fmamk_f32 v145, v145, 0x3a800000, v159
	v_fmamk_f32 v148, v148, 0x3a800000, v159
	v_rsq_f32_e32 v164, v148
	v_fmamk_f32 v150, v150, 0x3a800000, v159
	v_fmamk_f32 v152, v152, 0x3a800000, v159
	v_fmamk_f32 v165, v156, 0x3a800000, v159
	v_fmamk_f32 v167, v162, 0x3a800000, v159
	v_rsq_f32_e32 v162, v145
	v_fmamk_f32 v163, v163, 0x3a800000, v159
	v_rsq_f32_e32 v166, v150
	v_rsq_f32_e32 v156, v152
	v_pk_mul_f32 v[124:125], v[124:125], v[162:163] op_sel_hi:[1,0]
	v_pk_mul_f32 v[126:127], v[126:127], v[162:163] op_sel_hi:[1,0]
	v_pk_mul_f32 v[120:121], v[120:121], v[162:163] op_sel_hi:[1,0]
	v_pk_mul_f32 v[122:123], v[122:123], v[162:163] op_sel_hi:[1,0]
	v_rsq_f32_e32 v152, v165
	v_rsq_f32_e32 v150, v167
	v_rsq_f32_e32 v148, v163
	v_pk_mul_f32 v[112:113], v[112:113], v[162:163] op_sel_hi:[1,0]
	v_pk_mul_f32 v[114:115], v[114:115], v[162:163] op_sel_hi:[1,0]
	v_pk_mul_f32 v[108:109], v[108:109], v[162:163] op_sel_hi:[1,0]
	v_pk_mul_f32 v[110:111], v[110:111], v[162:163] op_sel_hi:[1,0]
	v_pk_mul_f32 v[116:117], v[116:117], v[164:165] op_sel_hi:[1,0]
	v_pk_mul_f32 v[100:101], v[100:101], v[164:165] op_sel_hi:[1,0]
	v_pk_mul_f32 v[118:119], v[118:119], v[164:165] op_sel_hi:[1,0]
	v_mul_f32_e32 v145, 0xbfb8aa3b, v124
	v_mul_f32_e32 v162, 0xbfb8aa3b, v125
	v_mul_f32_e32 v163, 0xbfb8aa3b, v126
	v_mul_f32_e32 v165, 0xbfb8aa3b, v127
	v_mul_f32_e32 v167, 0xbfb8aa3b, v120
	v_mul_f32_e32 v168, 0xbfb8aa3b, v121
	v_mul_f32_e32 v169, 0xbfb8aa3b, v122
	v_mul_f32_e32 v170, 0xbfb8aa3b, v123
	v_mul_f32_e32 v171, 0xbfb8aa3b, v116
	v_mul_f32_e32 v172, 0xbfb8aa3b, v117
	v_mul_f32_e32 v173, 0xbfb8aa3b, v118
	v_exp_f32_e32 v145, v145
	v_exp_f32_e32 v162, v162
	v_exp_f32_e32 v163, v163
	v_exp_f32_e32 v165, v165
	v_exp_f32_e32 v167, v167
	v_exp_f32_e32 v168, v168
	v_exp_f32_e32 v169, v169
	v_exp_f32_e32 v170, v170
	v_exp_f32_e32 v171, v171
	v_exp_f32_e32 v172, v172
	v_exp_f32_e32 v173, v173
	v_add_f32_e32 v145, 1.0, v145
	v_add_f32_e32 v175, 1.0, v162
	v_add_f32_e32 v176, 1.0, v163
	v_add_f32_e32 v165, 1.0, v165
	v_add_f32_e32 v167, 1.0, v167
	v_add_f32_e32 v177, 1.0, v168
	v_add_f32_e32 v178, 1.0, v169
	v_add_f32_e32 v179, 1.0, v170
	v_mul_f32_e32 v174, 0xbfb8aa3b, v119
	v_add_f32_e32 v180, 1.0, v171
	v_add_f32_e32 v181, 1.0, v172
	v_add_f32_e32 v182, 1.0, v173
	v_rcp_f32_e32 v162, v145
	v_rcp_f32_e32 v163, v175
	v_rcp_f32_e32 v168, v176
	v_rcp_f32_e32 v169, v165
	v_rcp_f32_e32 v170, v167
	v_rcp_f32_e32 v171, v177
	v_rcp_f32_e32 v172, v178
	v_rcp_f32_e32 v173, v179
	v_exp_f32_e32 v174, v174
	v_pk_mul_f32 v[124:125], v[124:125], v[162:163]
	v_pk_mul_f32 v[126:127], v[126:127], v[168:169]
	v_pk_mul_f32 v[120:121], v[120:121], v[170:171]
	v_pk_mul_f32 v[122:123], v[122:123], v[172:173]
	v_add_f32_e32 v183, 1.0, v174
	v_rcp_f32_e32 v174, v180
	v_rcp_f32_e32 v175, v181
	v_pk_mul_f32 v[112:113], v[112:113], v[124:125]
	v_pk_mul_f32 v[114:115], v[114:115], v[126:127]
	v_pk_mul_f32 v[120:121], v[108:109], v[120:121]
	v_pk_mul_f32 v[122:123], v[110:111], v[122:123]
	v_rcp_f32_e32 v176, v182
	v_cvt_pk_bf16_f32 v108, v112, v113
	v_cvt_pk_bf16_f32 v109, v114, v115
	v_cvt_pk_bf16_f32 v110, v120, v121
	v_cvt_pk_bf16_f32 v111, v122, v123
	v_rcp_f32_e32 v177, v183
	v_pk_mul_f32 v[104:105], v[104:105], v[164:165] op_sel_hi:[1,0]
	global_store_dwordx4 v[160:161], v[108:111], off
	v_pk_mul_f32 v[102:103], v[102:103], v[164:165] op_sel_hi:[1,0]
	v_pk_mul_f32 v[106:107], v[106:107], v[164:165] op_sel_hi:[1,0]
	v_mul_f32_e32 v110, 0xbfb8aa3b, v104
	v_exp_f32_e32 v110, v110
	v_pk_mul_f32 v[108:109], v[116:117], v[174:175]
	v_mul_f32_e32 v111, 0xbfb8aa3b, v107
	v_pk_mul_f32 v[100:101], v[100:101], v[108:109]
	v_pk_mul_f32 v[108:109], v[118:119], v[176:177]
	v_exp_f32_e32 v111, v111
	v_pk_mul_f32 v[102:103], v[102:103], v[108:109]
	v_mul_f32_e32 v108, 0xbfb8aa3b, v105
	v_exp_f32_e32 v109, v108
	v_add_f32_e32 v108, 1.0, v110
	v_mul_f32_e32 v110, 0xbfb8aa3b, v106
	v_exp_f32_e32 v110, v110
	v_add_f32_e32 v109, 1.0, v109
	v_rcp_f32_e32 v108, v108
	v_rcp_f32_e32 v109, v109
	v_add_f32_e32 v110, 1.0, v110
	v_add_f32_e32 v111, 1.0, v111
	v_rcp_f32_e32 v110, v110
	v_rcp_f32_e32 v111, v111
	v_pk_mul_f32 v[96:97], v[96:97], v[164:165] op_sel_hi:[1,0]
	v_pk_mul_f32 v[104:105], v[104:105], v[108:109]
	v_or_b32_e32 v108, 16, v144
	v_pk_mul_f32 v[104:105], v[96:97], v[104:105]
	v_pk_mul_f32 v[96:97], v[98:99], v[164:165] op_sel_hi:[1,0]
	v_pk_mul_f32 v[98:99], v[106:107], v[110:111]
	v_pk_mul_f32 v[92:93], v[92:93], v[166:167] op_sel_hi:[1,0]
	v_pk_mul_f32 v[106:107], v[96:97], v[98:99]
	v_cvt_pk_bf16_f32 v96, v100, v101
	v_cvt_pk_bf16_f32 v97, v102, v103
	v_cvt_pk_bf16_f32 v98, v104, v105
	v_cvt_pk_bf16_f32 v99, v106, v107
	v_mad_i64_i32 v[100:101], s[38:39], v108, s62, v[146:147]
	v_mul_f32_e32 v102, 0xbfb8aa3b, v92
	global_store_dwordx4 v[100:101], v[96:99], off
	v_pk_mul_f32 v[94:95], v[94:95], v[166:167] op_sel_hi:[1,0]
	v_exp_f32_e32 v102, v102
	v_mul_f32_e32 v96, 0xbfb8aa3b, v93
	v_exp_f32_e32 v97, v96
	v_mul_f32_e32 v98, 0xbfb8aa3b, v94
	v_mul_f32_e32 v99, 0xbfb8aa3b, v95
	v_exp_f32_e32 v98, v98
	v_exp_f32_e32 v99, v99
	v_add_f32_e32 v96, 1.0, v102
	v_add_f32_e32 v97, 1.0, v97
	v_rcp_f32_e32 v96, v96
	v_rcp_f32_e32 v97, v97
	v_add_f32_e32 v98, 1.0, v98
	v_add_f32_e32 v99, 1.0, v99
	v_rcp_f32_e32 v98, v98
	v_rcp_f32_e32 v99, v99
	v_pk_mul_f32 v[84:85], v[84:85], v[166:167] op_sel_hi:[1,0]
	v_pk_mul_f32 v[92:93], v[92:93], v[96:97]
	v_pk_mul_f32 v[88:89], v[88:89], v[166:167] op_sel_hi:[1,0]
	v_pk_mul_f32 v[84:85], v[84:85], v[92:93]
	v_pk_mul_f32 v[92:93], v[94:95], v[98:99]
	v_mul_f32_e32 v94, 0xbfb8aa3b, v88
	v_exp_f32_e32 v94, v94
	v_pk_mul_f32 v[86:87], v[86:87], v[166:167] op_sel_hi:[1,0]
	v_pk_mul_f32 v[90:91], v[90:91], v[166:167] op_sel_hi:[1,0]
	v_pk_mul_f32 v[86:87], v[86:87], v[92:93]
	v_mul_f32_e32 v92, 0xbfb8aa3b, v89
	v_exp_f32_e32 v93, v92
	v_add_f32_e32 v92, 1.0, v94
	v_mul_f32_e32 v94, 0xbfb8aa3b, v90
	v_mul_f32_e32 v95, 0xbfb8aa3b, v91
	v_exp_f32_e32 v94, v94
	v_exp_f32_e32 v95, v95
	v_add_f32_e32 v93, 1.0, v93
	v_rcp_f32_e32 v92, v92
	v_rcp_f32_e32 v93, v93
	v_add_f32_e32 v94, 1.0, v94
	v_add_f32_e32 v95, 1.0, v95
	v_rcp_f32_e32 v94, v94
	v_rcp_f32_e32 v95, v95
	v_pk_mul_f32 v[80:81], v[80:81], v[166:167] op_sel_hi:[1,0]
	v_pk_mul_f32 v[88:89], v[88:89], v[92:93]
	v_or_b32_e32 v92, 32, v144
	v_pk_mul_f32 v[88:89], v[80:81], v[88:89]
	v_pk_mul_f32 v[80:81], v[82:83], v[166:167] op_sel_hi:[1,0]
	v_pk_mul_f32 v[82:83], v[90:91], v[94:95]
	v_pk_mul_f32 v[76:77], v[76:77], v[156:157] op_sel_hi:[1,0]
	v_pk_mul_f32 v[90:91], v[80:81], v[82:83]
	v_cvt_pk_bf16_f32 v80, v84, v85
	v_cvt_pk_bf16_f32 v81, v86, v87
	v_cvt_pk_bf16_f32 v82, v88, v89
	v_cvt_pk_bf16_f32 v83, v90, v91
	v_mad_i64_i32 v[84:85], s[38:39], v92, s62, v[146:147]
	v_mul_f32_e32 v86, 0xbfb8aa3b, v76
	global_store_dwordx4 v[84:85], v[80:83], off
	v_pk_mul_f32 v[78:79], v[78:79], v[156:157] op_sel_hi:[1,0]
	v_exp_f32_e32 v86, v86
	v_mul_f32_e32 v80, 0xbfb8aa3b, v77
	v_exp_f32_e32 v81, v80
	v_mul_f32_e32 v82, 0xbfb8aa3b, v78
	v_mul_f32_e32 v83, 0xbfb8aa3b, v79
	v_exp_f32_e32 v82, v82
	v_exp_f32_e32 v83, v83
	v_add_f32_e32 v80, 1.0, v86
	v_add_f32_e32 v81, 1.0, v81
	v_rcp_f32_e32 v80, v80
	v_rcp_f32_e32 v81, v81
	v_add_f32_e32 v82, 1.0, v82
	v_add_f32_e32 v83, 1.0, v83
	v_rcp_f32_e32 v82, v82
	v_rcp_f32_e32 v83, v83
	v_pk_mul_f32 v[68:69], v[68:69], v[156:157] op_sel_hi:[1,0]
	v_pk_mul_f32 v[76:77], v[76:77], v[80:81]
	v_pk_mul_f32 v[72:73], v[72:73], v[156:157] op_sel_hi:[1,0]
	v_pk_mul_f32 v[68:69], v[68:69], v[76:77]
	v_pk_mul_f32 v[76:77], v[78:79], v[82:83]
	v_mul_f32_e32 v78, 0xbfb8aa3b, v72
	v_exp_f32_e32 v78, v78
	v_pk_mul_f32 v[70:71], v[70:71], v[156:157] op_sel_hi:[1,0]
	v_pk_mul_f32 v[74:75], v[74:75], v[156:157] op_sel_hi:[1,0]
	v_pk_mul_f32 v[70:71], v[70:71], v[76:77]
	v_mul_f32_e32 v76, 0xbfb8aa3b, v73
	v_exp_f32_e32 v77, v76
	v_add_f32_e32 v76, 1.0, v78
	v_mul_f32_e32 v78, 0xbfb8aa3b, v74
	v_mul_f32_e32 v79, 0xbfb8aa3b, v75
	v_exp_f32_e32 v78, v78
	v_exp_f32_e32 v79, v79
	v_add_f32_e32 v77, 1.0, v77
	v_rcp_f32_e32 v76, v76
	v_rcp_f32_e32 v77, v77
	v_add_f32_e32 v78, 1.0, v78
	v_add_f32_e32 v79, 1.0, v79
	v_rcp_f32_e32 v78, v78
	v_rcp_f32_e32 v79, v79
	v_fmamk_f32 v154, v154, 0x3a800000, v159
	v_rsq_f32_e32 v154, v154
	v_pk_mul_f32 v[64:65], v[64:65], v[156:157] op_sel_hi:[1,0]
	v_pk_mul_f32 v[72:73], v[72:73], v[76:77]
	v_or_b32_e32 v76, 48, v144
	v_pk_mul_f32 v[72:73], v[64:65], v[72:73]
	v_pk_mul_f32 v[64:65], v[66:67], v[156:157] op_sel_hi:[1,0]
	v_pk_mul_f32 v[66:67], v[74:75], v[78:79]
	v_pk_mul_f32 v[60:61], v[60:61], v[154:155] op_sel_hi:[1,0]
	v_pk_mul_f32 v[74:75], v[64:65], v[66:67]
	v_cvt_pk_bf16_f32 v64, v68, v69
	v_cvt_pk_bf16_f32 v65, v70, v71
	v_cvt_pk_bf16_f32 v66, v72, v73
	v_cvt_pk_bf16_f32 v67, v74, v75
	v_mad_i64_i32 v[68:69], s[38:39], v76, s62, v[146:147]
	global_store_dwordx4 v[68:69], v[64:67], off
	v_pk_mul_f32 v[62:63], v[62:63], v[154:155] op_sel_hi:[1,0]
	v_pk_mul_f32 v[52:53], v[52:53], v[154:155] op_sel_hi:[1,0]
	v_mul_f32_e32 v64, 0xbfb8aa3b, v60
	v_mul_f32_e32 v65, 0xbfb8aa3b, v61
	v_exp_f32_e32 v64, v64
	v_exp_f32_e32 v65, v65
	v_mul_f32_e32 v66, 0xbfb8aa3b, v62
	v_mul_f32_e32 v67, 0xbfb8aa3b, v63
	v_exp_f32_e32 v66, v66
	v_exp_f32_e32 v67, v67
	v_add_f32_e32 v64, 1.0, v64
	v_add_f32_e32 v65, 1.0, v65
	v_rcp_f32_e32 v64, v64
	v_rcp_f32_e32 v65, v65
	v_add_f32_e32 v66, 1.0, v66
	v_add_f32_e32 v67, 1.0, v67
	v_rcp_f32_e32 v66, v66
	v_rcp_f32_e32 v67, v67
	v_pk_mul_f32 v[60:61], v[60:61], v[64:65]
	v_pk_mul_f32 v[56:57], v[56:57], v[154:155] op_sel_hi:[1,0]
	v_pk_mul_f32 v[52:53], v[52:53], v[60:61]
	v_pk_mul_f32 v[60:61], v[62:63], v[66:67]
	v_mul_f32_e32 v62, 0xbfb8aa3b, v56
	v_exp_f32_e32 v62, v62
	v_pk_mul_f32 v[54:55], v[54:55], v[154:155] op_sel_hi:[1,0]
	v_pk_mul_f32 v[58:59], v[58:59], v[154:155] op_sel_hi:[1,0]
	v_pk_mul_f32 v[54:55], v[54:55], v[60:61]
	v_mul_f32_e32 v60, 0xbfb8aa3b, v57
	v_exp_f32_e32 v61, v60
	v_add_f32_e32 v60, 1.0, v62
	v_mul_f32_e32 v62, 0xbfb8aa3b, v58
	v_mul_f32_e32 v63, 0xbfb8aa3b, v59
	v_exp_f32_e32 v62, v62
	v_exp_f32_e32 v63, v63
	v_add_f32_e32 v61, 1.0, v61
	v_rcp_f32_e32 v60, v60
	v_rcp_f32_e32 v61, v61
	v_add_f32_e32 v62, 1.0, v62
	v_add_f32_e32 v63, 1.0, v63
	v_rcp_f32_e32 v62, v62
	v_rcp_f32_e32 v63, v63
	v_pk_mul_f32 v[48:49], v[48:49], v[154:155] op_sel_hi:[1,0]
	v_pk_mul_f32 v[56:57], v[56:57], v[60:61]
	v_add_u32_e32 v68, 0x80, v144
	v_pk_mul_f32 v[56:57], v[48:49], v[56:57]
	v_pk_mul_f32 v[48:49], v[50:51], v[154:155] op_sel_hi:[1,0]
	v_pk_mul_f32 v[50:51], v[58:59], v[62:63]
	v_pk_mul_f32 v[44:45], v[44:45], v[152:153] op_sel_hi:[1,0]
	v_pk_mul_f32 v[58:59], v[48:49], v[50:51]
	v_cvt_pk_bf16_f32 v48, v52, v53
	v_cvt_pk_bf16_f32 v49, v54, v55
	v_cvt_pk_bf16_f32 v50, v56, v57
	v_cvt_pk_bf16_f32 v51, v58, v59
	v_mad_i64_i32 v[52:53], s[38:39], v68, s62, v[146:147]
	v_mul_f32_e32 v54, 0xbfb8aa3b, v44
	global_store_dwordx4 v[52:53], v[48:51], off
	v_pk_mul_f32 v[46:47], v[46:47], v[152:153] op_sel_hi:[1,0]
	v_exp_f32_e32 v54, v54
	v_mul_f32_e32 v48, 0xbfb8aa3b, v45
	v_exp_f32_e32 v49, v48
	v_mul_f32_e32 v50, 0xbfb8aa3b, v46
	v_mul_f32_e32 v51, 0xbfb8aa3b, v47
	v_exp_f32_e32 v50, v50
	v_exp_f32_e32 v51, v51
	v_add_f32_e32 v48, 1.0, v54
	v_add_f32_e32 v49, 1.0, v49
	v_rcp_f32_e32 v48, v48
	v_rcp_f32_e32 v49, v49
	v_add_f32_e32 v50, 1.0, v50
	v_add_f32_e32 v51, 1.0, v51
	v_rcp_f32_e32 v50, v50
	v_rcp_f32_e32 v51, v51
	v_pk_mul_f32 v[36:37], v[36:37], v[152:153] op_sel_hi:[1,0]
	v_pk_mul_f32 v[44:45], v[44:45], v[48:49]
	v_pk_mul_f32 v[40:41], v[40:41], v[152:153] op_sel_hi:[1,0]
	v_pk_mul_f32 v[36:37], v[36:37], v[44:45]
	v_pk_mul_f32 v[44:45], v[46:47], v[50:51]
	v_mul_f32_e32 v46, 0xbfb8aa3b, v40
	v_exp_f32_e32 v46, v46
	v_pk_mul_f32 v[38:39], v[38:39], v[152:153] op_sel_hi:[1,0]
	v_pk_mul_f32 v[42:43], v[42:43], v[152:153] op_sel_hi:[1,0]
	v_pk_mul_f32 v[38:39], v[38:39], v[44:45]
	v_mul_f32_e32 v44, 0xbfb8aa3b, v41
	v_exp_f32_e32 v45, v44
	v_add_f32_e32 v44, 1.0, v46
	v_mul_f32_e32 v46, 0xbfb8aa3b, v42
	v_mul_f32_e32 v47, 0xbfb8aa3b, v43
	v_exp_f32_e32 v46, v46
	v_exp_f32_e32 v47, v47
	v_add_f32_e32 v45, 1.0, v45
	v_rcp_f32_e32 v44, v44
	v_rcp_f32_e32 v45, v45
	v_add_f32_e32 v46, 1.0, v46
	v_add_f32_e32 v47, 1.0, v47
	v_rcp_f32_e32 v46, v46
	v_rcp_f32_e32 v47, v47
	v_pk_mul_f32 v[32:33], v[32:33], v[152:153] op_sel_hi:[1,0]
	v_pk_mul_f32 v[40:41], v[40:41], v[44:45]
	v_add_u32_e32 v44, 0x90, v144
	v_pk_mul_f32 v[40:41], v[32:33], v[40:41]
	v_pk_mul_f32 v[32:33], v[34:35], v[152:153] op_sel_hi:[1,0]
	v_pk_mul_f32 v[34:35], v[42:43], v[46:47]
	v_pk_mul_f32 v[28:29], v[28:29], v[150:151] op_sel_hi:[1,0]
	v_pk_mul_f32 v[42:43], v[32:33], v[34:35]
	v_cvt_pk_bf16_f32 v32, v36, v37
	v_cvt_pk_bf16_f32 v33, v38, v39
	v_cvt_pk_bf16_f32 v34, v40, v41
	v_cvt_pk_bf16_f32 v35, v42, v43
	v_mad_i64_i32 v[36:37], s[38:39], v44, s62, v[146:147]
	v_mul_f32_e32 v38, 0xbfb8aa3b, v28
	global_store_dwordx4 v[36:37], v[32:35], off
	v_pk_mul_f32 v[30:31], v[30:31], v[150:151] op_sel_hi:[1,0]
	v_exp_f32_e32 v38, v38
	v_mul_f32_e32 v32, 0xbfb8aa3b, v29
	v_exp_f32_e32 v33, v32
	v_mul_f32_e32 v34, 0xbfb8aa3b, v30
	v_mul_f32_e32 v35, 0xbfb8aa3b, v31
	v_exp_f32_e32 v34, v34
	v_exp_f32_e32 v35, v35
	v_add_f32_e32 v32, 1.0, v38
	v_add_f32_e32 v33, 1.0, v33
	v_rcp_f32_e32 v32, v32
	v_rcp_f32_e32 v33, v33
	v_add_f32_e32 v34, 1.0, v34
	v_add_f32_e32 v35, 1.0, v35
	v_rcp_f32_e32 v34, v34
	v_rcp_f32_e32 v35, v35
	v_pk_mul_f32 v[20:21], v[20:21], v[150:151] op_sel_hi:[1,0]
	v_pk_mul_f32 v[28:29], v[28:29], v[32:33]
	v_pk_mul_f32 v[24:25], v[24:25], v[150:151] op_sel_hi:[1,0]
	v_pk_mul_f32 v[20:21], v[20:21], v[28:29]
	v_pk_mul_f32 v[28:29], v[30:31], v[34:35]
	v_mul_f32_e32 v30, 0xbfb8aa3b, v24
	v_exp_f32_e32 v30, v30
	v_pk_mul_f32 v[22:23], v[22:23], v[150:151] op_sel_hi:[1,0]
	v_pk_mul_f32 v[26:27], v[26:27], v[150:151] op_sel_hi:[1,0]
	v_pk_mul_f32 v[22:23], v[22:23], v[28:29]
	v_mul_f32_e32 v28, 0xbfb8aa3b, v25
	v_exp_f32_e32 v29, v28
	v_add_f32_e32 v28, 1.0, v30
	v_mul_f32_e32 v30, 0xbfb8aa3b, v26
	v_mul_f32_e32 v31, 0xbfb8aa3b, v27
	v_exp_f32_e32 v30, v30
	v_exp_f32_e32 v31, v31
	v_add_f32_e32 v29, 1.0, v29
	v_rcp_f32_e32 v28, v28
	v_rcp_f32_e32 v29, v29
	v_add_f32_e32 v30, 1.0, v30
	v_add_f32_e32 v31, 1.0, v31
	v_rcp_f32_e32 v30, v30
	v_rcp_f32_e32 v31, v31
	v_pk_mul_f32 v[16:17], v[16:17], v[150:151] op_sel_hi:[1,0]
	v_pk_mul_f32 v[24:25], v[24:25], v[28:29]
	v_add_u32_e32 v28, 0xa0, v144
	v_pk_mul_f32 v[24:25], v[16:17], v[24:25]
	v_pk_mul_f32 v[16:17], v[18:19], v[150:151] op_sel_hi:[1,0]
	v_pk_mul_f32 v[18:19], v[26:27], v[30:31]
	v_pk_mul_f32 v[12:13], v[12:13], v[148:149] op_sel_hi:[1,0]
	v_pk_mul_f32 v[26:27], v[16:17], v[18:19]
	v_cvt_pk_bf16_f32 v16, v20, v21
	v_cvt_pk_bf16_f32 v17, v22, v23
	v_cvt_pk_bf16_f32 v18, v24, v25
	v_cvt_pk_bf16_f32 v19, v26, v27
	v_mad_i64_i32 v[20:21], s[38:39], v28, s62, v[146:147]
	v_mul_f32_e32 v22, 0xbfb8aa3b, v12
	global_store_dwordx4 v[20:21], v[16:19], off
	v_pk_mul_f32 v[14:15], v[14:15], v[148:149] op_sel_hi:[1,0]
	v_exp_f32_e32 v22, v22
	v_mul_f32_e32 v16, 0xbfb8aa3b, v13
	v_exp_f32_e32 v17, v16
	v_mul_f32_e32 v18, 0xbfb8aa3b, v14
	v_mul_f32_e32 v19, 0xbfb8aa3b, v15
	v_exp_f32_e32 v18, v18
	v_exp_f32_e32 v19, v19
	v_add_f32_e32 v16, 1.0, v22
	v_add_f32_e32 v17, 1.0, v17
	v_rcp_f32_e32 v16, v16
	v_rcp_f32_e32 v17, v17
	v_add_f32_e32 v18, 1.0, v18
	v_add_f32_e32 v19, 1.0, v19
	v_rcp_f32_e32 v18, v18
	v_rcp_f32_e32 v19, v19
	v_pk_mul_f32 v[4:5], v[4:5], v[148:149] op_sel_hi:[1,0]
	v_pk_mul_f32 v[12:13], v[12:13], v[16:17]
	v_pk_mul_f32 v[8:9], v[8:9], v[148:149] op_sel_hi:[1,0]
	v_pk_mul_f32 v[4:5], v[4:5], v[12:13]
	v_pk_mul_f32 v[12:13], v[14:15], v[18:19]
	v_mul_f32_e32 v14, 0xbfb8aa3b, v8
	v_exp_f32_e32 v14, v14
	v_pk_mul_f32 v[6:7], v[6:7], v[148:149] op_sel_hi:[1,0]
	v_pk_mul_f32 v[10:11], v[10:11], v[148:149] op_sel_hi:[1,0]
	v_pk_mul_f32 v[6:7], v[6:7], v[12:13]
	v_mul_f32_e32 v12, 0xbfb8aa3b, v9
	v_exp_f32_e32 v13, v12
	v_add_f32_e32 v12, 1.0, v14
	v_mul_f32_e32 v14, 0xbfb8aa3b, v10
	v_mul_f32_e32 v15, 0xbfb8aa3b, v11
	v_exp_f32_e32 v14, v14
	v_exp_f32_e32 v15, v15
	v_add_f32_e32 v13, 1.0, v13
	v_rcp_f32_e32 v12, v12
	v_rcp_f32_e32 v13, v13
	v_add_f32_e32 v14, 1.0, v14
	v_add_f32_e32 v15, 1.0, v15
	v_rcp_f32_e32 v14, v14
	v_rcp_f32_e32 v15, v15
	v_pk_mul_f32 v[0:1], v[0:1], v[148:149] op_sel_hi:[1,0]
	v_pk_mul_f32 v[8:9], v[8:9], v[12:13]
	v_add_u32_e32 v12, 0xb0, v144
	v_pk_mul_f32 v[8:9], v[0:1], v[8:9]
	v_pk_mul_f32 v[0:1], v[2:3], v[148:149] op_sel_hi:[1,0]
	v_pk_mul_f32 v[2:3], v[10:11], v[14:15]
	s_nop 0
	v_pk_mul_f32 v[10:11], v[0:1], v[2:3]
	v_cvt_pk_bf16_f32 v0, v4, v5
	v_cvt_pk_bf16_f32 v1, v6, v7
	v_cvt_pk_bf16_f32 v2, v8, v9
	v_cvt_pk_bf16_f32 v3, v10, v11
	v_mad_i64_i32 v[4:5], s[38:39], v12, s62, v[146:147]
	global_store_dwordx4 v[4:5], v[0:3], off
	s_cbranch_vccnz .LBB0_1111
	s_andn2_b64 vcc, exec, s[8:9]
	s_cbranch_vccnz .LBB0_1110
	s_barrier
	s_branch .LBB0_1110

.LBB0_1417:
	s_nop 0
	v_lshl_add_u32 v128, s36, 8, v163
	v_ashrrev_i32_e32 v129, 31, v128
	v_lshl_add_u64 v[130:131], v[128:129], 2, s[10:11]
	global_load_dword v129, v[130:131], off
	global_load_dword v132, v[130:131], off offset:64
	global_load_dword v133, v[130:131], off offset:128
	global_load_dword v134, v[130:131], off offset:192
	global_load_dword v135, v[130:131], off offset:512
	global_load_dword v160, v[130:131], off offset:576
	global_load_dword v161, v[130:131], off offset:640
	global_load_dword v162, v[130:131], off offset:704
	v_lshl_add_u32 v144, s80, 7, v167
	v_lshl_add_u64 v[130:131], v[144:145], 1, s[68:69]
	v_mad_i64_i32 v[168:169], s[14:15], v128, s75, v[130:131]
	s_waitcnt vmcnt(0)
	v_fmamk_f32 v129, v129, 0x3a800000, v176
	v_fmamk_f32 v132, v132, 0x3a800000, v176
	v_rsq_f32_e32 v170, v129
	v_rsq_f32_e32 v166, v132
	v_fmamk_f32 v133, v133, 0x3a800000, v176
	v_fmamk_f32 v134, v134, 0x3a800000, v176
	v_fmamk_f32 v135, v135, 0x3a800000, v176
	v_fmamk_f32 v161, v161, 0x3a800000, v176
	v_fmamk_f32 v172, v162, 0x3a800000, v176
	v_pk_mul_f32 v[124:125], v[124:125], v[170:171] op_sel_hi:[1,0]
	v_pk_mul_f32 v[126:127], v[126:127], v[170:171] op_sel_hi:[1,0]
	v_pk_mul_f32 v[120:121], v[120:121], v[170:171] op_sel_hi:[1,0]
	v_pk_mul_f32 v[122:123], v[122:123], v[170:171] op_sel_hi:[1,0]
	v_fmamk_f32 v144, v160, 0x3a800000, v176
	v_rsq_f32_e32 v164, v133
	v_rsq_f32_e32 v162, v134
	v_rsq_f32_e32 v160, v135
	v_rsq_f32_e32 v134, v161
	v_rsq_f32_e32 v132, v172
	v_pk_mul_f32 v[116:117], v[116:117], v[170:171] op_sel_hi:[1,0]
	v_pk_mul_f32 v[118:119], v[118:119], v[170:171] op_sel_hi:[1,0]
	v_pk_mul_f32 v[112:113], v[112:113], v[170:171] op_sel_hi:[1,0]
	v_pk_mul_f32 v[114:115], v[114:115], v[170:171] op_sel_hi:[1,0]
	v_pk_mul_f32 v[108:109], v[108:109], v[166:167] op_sel_hi:[1,0]
	v_pk_mul_f32 v[178:179], v[104:105], v[166:167] op_sel_hi:[1,0]
	v_pk_mul_f32 v[104:105], v[110:111], v[166:167] op_sel_hi:[1,0]
	v_mul_f32_e32 v110, 0xbfb8aa3b, v124
	v_mul_f32_e32 v111, 0xbfb8aa3b, v125
	v_mul_f32_e32 v129, 0xbfb8aa3b, v126
	v_mul_f32_e32 v133, 0xbfb8aa3b, v127
	v_mul_f32_e32 v135, 0xbfb8aa3b, v120
	v_mul_f32_e32 v161, 0xbfb8aa3b, v121
	v_mul_f32_e32 v170, 0xbfb8aa3b, v122
	v_mul_f32_e32 v172, 0xbfb8aa3b, v123
	v_mul_f32_e32 v180, 0xbfb8aa3b, v109
	v_mul_f32_e32 v181, 0xbfb8aa3b, v104
	v_mul_f32_e32 v182, 0xbfb8aa3b, v105
	v_exp_f32_e32 v110, v110
	v_exp_f32_e32 v111, v111
	v_exp_f32_e32 v129, v129
	v_exp_f32_e32 v133, v133
	v_exp_f32_e32 v135, v135
	v_exp_f32_e32 v161, v161
	v_exp_f32_e32 v170, v170
	v_exp_f32_e32 v172, v172
	v_exp_f32_e32 v180, v180
	v_exp_f32_e32 v181, v181
	v_exp_f32_e32 v182, v182
	v_add_f32_e32 v110, 1.0, v110
	v_add_f32_e32 v111, 1.0, v111
	v_add_f32_e32 v129, 1.0, v129
	v_add_f32_e32 v133, 1.0, v133
	v_add_f32_e32 v135, 1.0, v135
	v_add_f32_e32 v161, 1.0, v161
	v_add_f32_e32 v170, 1.0, v170
	v_add_f32_e32 v172, 1.0, v172
	v_add_f32_e32 v189, 1.0, v180
	v_add_f32_e32 v190, 1.0, v181
	v_add_f32_e32 v191, 1.0, v182
	v_rcp_f32_e32 v110, v110
	v_rcp_f32_e32 v111, v111
	v_rcp_f32_e32 v180, v129
	v_rcp_f32_e32 v181, v133
	v_rcp_f32_e32 v182, v135
	v_rcp_f32_e32 v183, v161
	v_rcp_f32_e32 v186, v170
	v_rcp_f32_e32 v187, v172
	v_pk_mul_f32 v[110:111], v[124:125], v[110:111]
	v_pk_mul_f32 v[124:125], v[126:127], v[180:181]
	v_pk_mul_f32 v[120:121], v[120:121], v[182:183]
	v_pk_mul_f32 v[122:123], v[122:123], v[186:187]
	v_pk_mul_f32 v[110:111], v[116:117], v[110:111]
	v_pk_mul_f32 v[116:117], v[118:119], v[124:125]
	v_pk_mul_f32 v[112:113], v[112:113], v[120:121]
	v_pk_mul_f32 v[114:115], v[114:115], v[122:123]
	v_rcp_f32_e32 v190, v190
	v_rcp_f32_e32 v191, v191
	v_cvt_pk_bf16_f32 v110, v110, v111
	v_cvt_pk_bf16_f32 v111, v116, v117
	v_cvt_pk_bf16_f32 v112, v112, v113
	v_cvt_pk_bf16_f32 v113, v114, v115
	v_pk_mul_f32 v[100:101], v[100:101], v[166:167] op_sel_hi:[1,0]
	global_store_dwordx4 v[168:169], v[110:113], off
	v_pk_mul_f32 v[106:107], v[106:107], v[166:167] op_sel_hi:[1,0]
	v_pk_mul_f32 v[104:105], v[104:105], v[190:191]
	v_mul_f32_e32 v110, 0xbfb8aa3b, v100
	v_exp_f32_e32 v110, v110
	v_pk_mul_f32 v[104:105], v[106:107], v[104:105]
	v_mul_f32_e32 v106, 0xbfb8aa3b, v101
	v_pk_mul_f32 v[102:103], v[102:103], v[166:167] op_sel_hi:[1,0]
	v_mul_f32_e32 v174, 0xbfb8aa3b, v108
	v_exp_f32_e32 v107, v106
	v_add_f32_e32 v106, 1.0, v110
	v_mul_f32_e32 v110, 0xbfb8aa3b, v102
	v_mul_f32_e32 v111, 0xbfb8aa3b, v103
	v_exp_f32_e32 v174, v174
	v_exp_f32_e32 v110, v110
	v_exp_f32_e32 v111, v111
	v_add_f32_e32 v107, 1.0, v107
	v_add_f32_e32 v174, 1.0, v174
	v_rcp_f32_e32 v106, v106
	v_rcp_f32_e32 v107, v107
	v_add_f32_e32 v110, 1.0, v110
	v_add_f32_e32 v111, 1.0, v111
	v_rcp_f32_e32 v188, v174
	v_rcp_f32_e32 v189, v189
	v_rcp_f32_e32 v110, v110
	v_rcp_f32_e32 v111, v111
	v_pk_mul_f32 v[96:97], v[96:97], v[166:167] op_sel_hi:[1,0]
	v_pk_mul_f32 v[100:101], v[100:101], v[106:107]
	v_pk_mul_f32 v[108:109], v[108:109], v[188:189]
	v_pk_mul_f32 v[100:101], v[96:97], v[100:101]
	v_pk_mul_f32 v[96:97], v[98:99], v[166:167] op_sel_hi:[1,0]
	v_pk_mul_f32 v[98:99], v[102:103], v[110:111]
	v_pk_mul_f32 v[108:109], v[178:179], v[108:109]
	v_pk_mul_f32 v[102:103], v[96:97], v[98:99]
	v_or_b32_e32 v106, 16, v128
	v_cvt_pk_bf16_f32 v96, v108, v109
	v_cvt_pk_bf16_f32 v97, v104, v105
	v_cvt_pk_bf16_f32 v98, v100, v101
	v_cvt_pk_bf16_f32 v99, v102, v103
	v_mad_i64_i32 v[100:101], s[14:15], v106, s75, v[130:131]
	v_pk_mul_f32 v[92:93], v[92:93], v[164:165] op_sel_hi:[1,0]
	global_store_dwordx4 v[100:101], v[96:99], off
	v_mul_f32_e32 v102, 0xbfb8aa3b, v92
	v_pk_mul_f32 v[94:95], v[94:95], v[164:165] op_sel_hi:[1,0]
	v_mul_f32_e32 v96, 0xbfb8aa3b, v93
	v_exp_f32_e32 v102, v102
	v_exp_f32_e32 v97, v96
	v_mul_f32_e32 v98, 0xbfb8aa3b, v94
	v_mul_f32_e32 v99, 0xbfb8aa3b, v95
	v_exp_f32_e32 v98, v98
	v_exp_f32_e32 v99, v99
	v_add_f32_e32 v96, 1.0, v102
	v_add_f32_e32 v97, 1.0, v97
	v_rcp_f32_e32 v96, v96
	v_rcp_f32_e32 v97, v97
	v_add_f32_e32 v98, 1.0, v98
	v_add_f32_e32 v99, 1.0, v99
	v_rcp_f32_e32 v98, v98
	v_rcp_f32_e32 v99, v99
	v_pk_mul_f32 v[88:89], v[88:89], v[164:165] op_sel_hi:[1,0]
	v_pk_mul_f32 v[92:93], v[92:93], v[96:97]
	v_pk_mul_f32 v[84:85], v[84:85], v[164:165] op_sel_hi:[1,0]
	v_pk_mul_f32 v[88:89], v[88:89], v[92:93]
	v_pk_mul_f32 v[92:93], v[94:95], v[98:99]
	v_mul_f32_e32 v94, 0xbfb8aa3b, v84
	v_exp_f32_e32 v94, v94
	v_pk_mul_f32 v[90:91], v[90:91], v[164:165] op_sel_hi:[1,0]
	v_pk_mul_f32 v[86:87], v[86:87], v[164:165] op_sel_hi:[1,0]
	v_pk_mul_f32 v[90:91], v[90:91], v[92:93]
	v_mul_f32_e32 v92, 0xbfb8aa3b, v85
	v_exp_f32_e32 v93, v92
	v_add_f32_e32 v92, 1.0, v94
	v_mul_f32_e32 v94, 0xbfb8aa3b, v86
	v_mul_f32_e32 v95, 0xbfb8aa3b, v87
	v_exp_f32_e32 v94, v94
	v_exp_f32_e32 v95, v95
	v_add_f32_e32 v93, 1.0, v93
	v_rcp_f32_e32 v92, v92
	v_rcp_f32_e32 v93, v93
	v_add_f32_e32 v94, 1.0, v94
	v_add_f32_e32 v95, 1.0, v95
	v_rcp_f32_e32 v94, v94
	v_rcp_f32_e32 v95, v95
	v_pk_mul_f32 v[80:81], v[80:81], v[164:165] op_sel_hi:[1,0]
	v_pk_mul_f32 v[84:85], v[84:85], v[92:93]
	v_or_b32_e32 v92, 32, v128
	v_pk_mul_f32 v[84:85], v[80:81], v[84:85]
	v_pk_mul_f32 v[80:81], v[82:83], v[164:165] op_sel_hi:[1,0]
	v_pk_mul_f32 v[82:83], v[86:87], v[94:95]
	v_pk_mul_f32 v[76:77], v[76:77], v[162:163] op_sel_hi:[1,0]
	v_pk_mul_f32 v[86:87], v[80:81], v[82:83]
	v_cvt_pk_bf16_f32 v80, v88, v89
	v_cvt_pk_bf16_f32 v81, v90, v91
	v_cvt_pk_bf16_f32 v82, v84, v85
	v_cvt_pk_bf16_f32 v83, v86, v87
	v_mad_i64_i32 v[84:85], s[14:15], v92, s75, v[130:131]
	v_mul_f32_e32 v86, 0xbfb8aa3b, v76
	global_store_dwordx4 v[84:85], v[80:83], off
	v_pk_mul_f32 v[78:79], v[78:79], v[162:163] op_sel_hi:[1,0]
	v_exp_f32_e32 v86, v86
	v_mul_f32_e32 v80, 0xbfb8aa3b, v77
	v_exp_f32_e32 v81, v80
	v_mul_f32_e32 v82, 0xbfb8aa3b, v78
	v_mul_f32_e32 v83, 0xbfb8aa3b, v79
	v_exp_f32_e32 v82, v82
	v_exp_f32_e32 v83, v83
	v_add_f32_e32 v80, 1.0, v86
	v_add_f32_e32 v81, 1.0, v81
	v_rcp_f32_e32 v80, v80
	v_rcp_f32_e32 v81, v81
	v_add_f32_e32 v82, 1.0, v82
	v_add_f32_e32 v83, 1.0, v83
	v_rcp_f32_e32 v82, v82
	v_rcp_f32_e32 v83, v83
	v_pk_mul_f32 v[72:73], v[72:73], v[162:163] op_sel_hi:[1,0]
	v_pk_mul_f32 v[76:77], v[76:77], v[80:81]
	v_pk_mul_f32 v[68:69], v[68:69], v[162:163] op_sel_hi:[1,0]
	v_pk_mul_f32 v[72:73], v[72:73], v[76:77]
	v_pk_mul_f32 v[76:77], v[78:79], v[82:83]
	v_mul_f32_e32 v78, 0xbfb8aa3b, v68
	v_exp_f32_e32 v78, v78
	v_pk_mul_f32 v[74:75], v[74:75], v[162:163] op_sel_hi:[1,0]
	v_pk_mul_f32 v[70:71], v[70:71], v[162:163] op_sel_hi:[1,0]
	v_pk_mul_f32 v[74:75], v[74:75], v[76:77]
	v_mul_f32_e32 v76, 0xbfb8aa3b, v69
	v_exp_f32_e32 v77, v76
	v_add_f32_e32 v76, 1.0, v78
	v_mul_f32_e32 v78, 0xbfb8aa3b, v70
	v_mul_f32_e32 v79, 0xbfb8aa3b, v71
	v_exp_f32_e32 v78, v78
	v_exp_f32_e32 v79, v79
	v_add_f32_e32 v77, 1.0, v77
	v_rcp_f32_e32 v76, v76
	v_rcp_f32_e32 v77, v77
	v_add_f32_e32 v78, 1.0, v78
	v_add_f32_e32 v79, 1.0, v79
	v_rcp_f32_e32 v78, v78
	v_rcp_f32_e32 v79, v79
	v_pk_mul_f32 v[64:65], v[64:65], v[162:163] op_sel_hi:[1,0]
	v_pk_mul_f32 v[68:69], v[68:69], v[76:77]
	v_or_b32_e32 v76, 48, v128
	v_pk_mul_f32 v[68:69], v[64:65], v[68:69]
	v_pk_mul_f32 v[64:65], v[66:67], v[162:163] op_sel_hi:[1,0]
	v_pk_mul_f32 v[66:67], v[70:71], v[78:79]
	v_pk_mul_f32 v[60:61], v[60:61], v[160:161] op_sel_hi:[1,0]
	v_pk_mul_f32 v[70:71], v[64:65], v[66:67]
	v_cvt_pk_bf16_f32 v64, v72, v73
	v_cvt_pk_bf16_f32 v65, v74, v75
	v_cvt_pk_bf16_f32 v66, v68, v69
	v_cvt_pk_bf16_f32 v67, v70, v71
	v_mad_i64_i32 v[68:69], s[14:15], v76, s75, v[130:131]
	global_store_dwordx4 v[68:69], v[64:67], off
	v_pk_mul_f32 v[62:63], v[62:63], v[160:161] op_sel_hi:[1,0]
	v_pk_mul_f32 v[56:57], v[56:57], v[160:161] op_sel_hi:[1,0]
	v_mul_f32_e32 v64, 0xbfb8aa3b, v60
	v_mul_f32_e32 v65, 0xbfb8aa3b, v61
	v_exp_f32_e32 v64, v64
	v_exp_f32_e32 v65, v65
	v_mul_f32_e32 v66, 0xbfb8aa3b, v62
	v_mul_f32_e32 v67, 0xbfb8aa3b, v63
	v_exp_f32_e32 v66, v66
	v_exp_f32_e32 v67, v67
	v_add_f32_e32 v64, 1.0, v64
	v_add_f32_e32 v65, 1.0, v65
	v_rcp_f32_e32 v64, v64
	v_rcp_f32_e32 v65, v65
	v_add_f32_e32 v66, 1.0, v66
	v_add_f32_e32 v67, 1.0, v67
	v_rcp_f32_e32 v66, v66
	v_rcp_f32_e32 v67, v67
	v_pk_mul_f32 v[60:61], v[60:61], v[64:65]
	v_pk_mul_f32 v[52:53], v[52:53], v[160:161] op_sel_hi:[1,0]
	v_pk_mul_f32 v[56:57], v[56:57], v[60:61]
	v_pk_mul_f32 v[60:61], v[62:63], v[66:67]
	v_mul_f32_e32 v62, 0xbfb8aa3b, v52
	v_exp_f32_e32 v62, v62
	v_pk_mul_f32 v[58:59], v[58:59], v[160:161] op_sel_hi:[1,0]
	v_pk_mul_f32 v[54:55], v[54:55], v[160:161] op_sel_hi:[1,0]
	v_pk_mul_f32 v[58:59], v[58:59], v[60:61]
	v_mul_f32_e32 v60, 0xbfb8aa3b, v53
	v_exp_f32_e32 v61, v60
	v_add_f32_e32 v60, 1.0, v62
	v_mul_f32_e32 v62, 0xbfb8aa3b, v54
	v_mul_f32_e32 v63, 0xbfb8aa3b, v55
	v_exp_f32_e32 v62, v62
	v_exp_f32_e32 v63, v63
	v_add_f32_e32 v61, 1.0, v61
	v_rcp_f32_e32 v60, v60
	v_rcp_f32_e32 v61, v61
	v_add_f32_e32 v62, 1.0, v62
	v_add_f32_e32 v63, 1.0, v63
	v_rcp_f32_e32 v62, v62
	v_rcp_f32_e32 v63, v63
	v_rsq_f32_e32 v144, v144
	v_pk_mul_f32 v[48:49], v[48:49], v[160:161] op_sel_hi:[1,0]
	v_pk_mul_f32 v[52:53], v[52:53], v[60:61]
	v_add_u32_e32 v68, 0x80, v128
	v_pk_mul_f32 v[52:53], v[48:49], v[52:53]
	v_pk_mul_f32 v[48:49], v[50:51], v[160:161] op_sel_hi:[1,0]
	v_pk_mul_f32 v[50:51], v[54:55], v[62:63]
	v_pk_mul_f32 v[44:45], v[44:45], v[144:145] op_sel_hi:[1,0]
	v_pk_mul_f32 v[54:55], v[48:49], v[50:51]
	v_cvt_pk_bf16_f32 v48, v56, v57
	v_cvt_pk_bf16_f32 v49, v58, v59
	v_cvt_pk_bf16_f32 v50, v52, v53
	v_cvt_pk_bf16_f32 v51, v54, v55
	v_mad_i64_i32 v[52:53], s[14:15], v68, s75, v[130:131]
	v_mul_f32_e32 v54, 0xbfb8aa3b, v44
	global_store_dwordx4 v[52:53], v[48:51], off
	v_pk_mul_f32 v[46:47], v[46:47], v[144:145] op_sel_hi:[1,0]
	v_exp_f32_e32 v54, v54
	v_mul_f32_e32 v48, 0xbfb8aa3b, v45
	v_exp_f32_e32 v49, v48
	v_mul_f32_e32 v50, 0xbfb8aa3b, v46
	v_mul_f32_e32 v51, 0xbfb8aa3b, v47
	v_exp_f32_e32 v50, v50
	v_exp_f32_e32 v51, v51
	v_add_f32_e32 v48, 1.0, v54
	v_add_f32_e32 v49, 1.0, v49
	v_rcp_f32_e32 v48, v48
	v_rcp_f32_e32 v49, v49
	v_add_f32_e32 v50, 1.0, v50
	v_add_f32_e32 v51, 1.0, v51
	v_rcp_f32_e32 v50, v50
	v_rcp_f32_e32 v51, v51
	v_pk_mul_f32 v[40:41], v[40:41], v[144:145] op_sel_hi:[1,0]
	v_pk_mul_f32 v[44:45], v[44:45], v[48:49]
	v_pk_mul_f32 v[36:37], v[36:37], v[144:145] op_sel_hi:[1,0]
	v_pk_mul_f32 v[40:41], v[40:41], v[44:45]
	v_pk_mul_f32 v[44:45], v[46:47], v[50:51]
	v_mul_f32_e32 v46, 0xbfb8aa3b, v36
	v_exp_f32_e32 v46, v46
	v_pk_mul_f32 v[42:43], v[42:43], v[144:145] op_sel_hi:[1,0]
	v_pk_mul_f32 v[38:39], v[38:39], v[144:145] op_sel_hi:[1,0]
	v_pk_mul_f32 v[42:43], v[42:43], v[44:45]
	v_mul_f32_e32 v44, 0xbfb8aa3b, v37
	v_exp_f32_e32 v45, v44
	v_add_f32_e32 v44, 1.0, v46
	v_mul_f32_e32 v46, 0xbfb8aa3b, v38
	v_mul_f32_e32 v47, 0xbfb8aa3b, v39
	v_exp_f32_e32 v46, v46
	v_exp_f32_e32 v47, v47
	v_add_f32_e32 v45, 1.0, v45
	v_rcp_f32_e32 v44, v44
	v_rcp_f32_e32 v45, v45
	v_add_f32_e32 v46, 1.0, v46
	v_add_f32_e32 v47, 1.0, v47
	v_rcp_f32_e32 v46, v46
	v_rcp_f32_e32 v47, v47
	v_pk_mul_f32 v[32:33], v[32:33], v[144:145] op_sel_hi:[1,0]
	v_pk_mul_f32 v[36:37], v[36:37], v[44:45]
	v_add_u32_e32 v44, 0x90, v128
	v_pk_mul_f32 v[36:37], v[32:33], v[36:37]
	v_pk_mul_f32 v[32:33], v[34:35], v[144:145] op_sel_hi:[1,0]
	v_pk_mul_f32 v[34:35], v[38:39], v[46:47]
	v_pk_mul_f32 v[28:29], v[28:29], v[134:135] op_sel_hi:[1,0]
	v_pk_mul_f32 v[38:39], v[32:33], v[34:35]
	v_cvt_pk_bf16_f32 v32, v40, v41
	v_cvt_pk_bf16_f32 v33, v42, v43
	v_cvt_pk_bf16_f32 v34, v36, v37
	v_cvt_pk_bf16_f32 v35, v38, v39
	v_mad_i64_i32 v[36:37], s[14:15], v44, s75, v[130:131]
	v_mul_f32_e32 v38, 0xbfb8aa3b, v28
	global_store_dwordx4 v[36:37], v[32:35], off
	v_pk_mul_f32 v[30:31], v[30:31], v[134:135] op_sel_hi:[1,0]
	v_exp_f32_e32 v38, v38
	v_mul_f32_e32 v32, 0xbfb8aa3b, v29
	v_exp_f32_e32 v33, v32
	v_mul_f32_e32 v34, 0xbfb8aa3b, v30
	v_mul_f32_e32 v35, 0xbfb8aa3b, v31
	v_exp_f32_e32 v34, v34
	v_exp_f32_e32 v35, v35
	v_add_f32_e32 v32, 1.0, v38
	v_add_f32_e32 v33, 1.0, v33
	v_rcp_f32_e32 v32, v32
	v_rcp_f32_e32 v33, v33
	v_add_f32_e32 v34, 1.0, v34
	v_add_f32_e32 v35, 1.0, v35
	v_rcp_f32_e32 v34, v34
	v_rcp_f32_e32 v35, v35
	v_pk_mul_f32 v[24:25], v[24:25], v[134:135] op_sel_hi:[1,0]
	v_pk_mul_f32 v[28:29], v[28:29], v[32:33]
	v_pk_mul_f32 v[20:21], v[20:21], v[134:135] op_sel_hi:[1,0]
	v_pk_mul_f32 v[24:25], v[24:25], v[28:29]
	v_pk_mul_f32 v[28:29], v[30:31], v[34:35]
	v_mul_f32_e32 v30, 0xbfb8aa3b, v20
	v_exp_f32_e32 v30, v30
	v_pk_mul_f32 v[26:27], v[26:27], v[134:135] op_sel_hi:[1,0]
	v_pk_mul_f32 v[22:23], v[22:23], v[134:135] op_sel_hi:[1,0]
	v_pk_mul_f32 v[26:27], v[26:27], v[28:29]
	v_mul_f32_e32 v28, 0xbfb8aa3b, v21
	v_exp_f32_e32 v29, v28
	v_add_f32_e32 v28, 1.0, v30
	v_mul_f32_e32 v30, 0xbfb8aa3b, v22
	v_mul_f32_e32 v31, 0xbfb8aa3b, v23
	v_exp_f32_e32 v30, v30
	v_exp_f32_e32 v31, v31
	v_add_f32_e32 v29, 1.0, v29
	v_rcp_f32_e32 v28, v28
	v_rcp_f32_e32 v29, v29
	v_add_f32_e32 v30, 1.0, v30
	v_add_f32_e32 v31, 1.0, v31
	v_rcp_f32_e32 v30, v30
	v_rcp_f32_e32 v31, v31
	v_pk_mul_f32 v[16:17], v[16:17], v[134:135] op_sel_hi:[1,0]
	v_pk_mul_f32 v[20:21], v[20:21], v[28:29]
	v_add_u32_e32 v28, 0xa0, v128
	v_pk_mul_f32 v[20:21], v[16:17], v[20:21]
	v_pk_mul_f32 v[16:17], v[18:19], v[134:135] op_sel_hi:[1,0]
	v_pk_mul_f32 v[18:19], v[22:23], v[30:31]
	v_pk_mul_f32 v[12:13], v[12:13], v[132:133] op_sel_hi:[1,0]
	v_pk_mul_f32 v[22:23], v[16:17], v[18:19]
	v_cvt_pk_bf16_f32 v16, v24, v25
	v_cvt_pk_bf16_f32 v17, v26, v27
	v_cvt_pk_bf16_f32 v18, v20, v21
	v_cvt_pk_bf16_f32 v19, v22, v23
	v_mad_i64_i32 v[20:21], s[14:15], v28, s75, v[130:131]
	v_mul_f32_e32 v22, 0xbfb8aa3b, v12
	global_store_dwordx4 v[20:21], v[16:19], off
	v_pk_mul_f32 v[14:15], v[14:15], v[132:133] op_sel_hi:[1,0]
	v_exp_f32_e32 v22, v22
	v_mul_f32_e32 v16, 0xbfb8aa3b, v13
	v_exp_f32_e32 v17, v16
	v_mul_f32_e32 v18, 0xbfb8aa3b, v14
	v_mul_f32_e32 v19, 0xbfb8aa3b, v15
	v_exp_f32_e32 v18, v18
	v_exp_f32_e32 v19, v19
	v_add_f32_e32 v16, 1.0, v22
	v_add_f32_e32 v17, 1.0, v17
	v_rcp_f32_e32 v16, v16
	v_rcp_f32_e32 v17, v17
	v_add_f32_e32 v18, 1.0, v18
	v_add_f32_e32 v19, 1.0, v19
	v_rcp_f32_e32 v18, v18
	v_rcp_f32_e32 v19, v19
	v_pk_mul_f32 v[8:9], v[8:9], v[132:133] op_sel_hi:[1,0]
	v_pk_mul_f32 v[12:13], v[12:13], v[16:17]
	v_pk_mul_f32 v[4:5], v[4:5], v[132:133] op_sel_hi:[1,0]
	v_pk_mul_f32 v[8:9], v[8:9], v[12:13]
	v_pk_mul_f32 v[12:13], v[14:15], v[18:19]
	v_mul_f32_e32 v14, 0xbfb8aa3b, v4
	v_exp_f32_e32 v14, v14
	v_pk_mul_f32 v[10:11], v[10:11], v[132:133] op_sel_hi:[1,0]
	v_pk_mul_f32 v[6:7], v[6:7], v[132:133] op_sel_hi:[1,0]
	v_pk_mul_f32 v[10:11], v[10:11], v[12:13]
	v_mul_f32_e32 v12, 0xbfb8aa3b, v5
	v_exp_f32_e32 v13, v12
	v_add_f32_e32 v12, 1.0, v14
	v_mul_f32_e32 v14, 0xbfb8aa3b, v6
	v_mul_f32_e32 v15, 0xbfb8aa3b, v7
	v_exp_f32_e32 v14, v14
	v_exp_f32_e32 v15, v15
	v_add_f32_e32 v13, 1.0, v13
	v_rcp_f32_e32 v12, v12
	v_rcp_f32_e32 v13, v13
	v_add_f32_e32 v14, 1.0, v14
	v_add_f32_e32 v15, 1.0, v15
	v_rcp_f32_e32 v14, v14
	v_rcp_f32_e32 v15, v15
	v_pk_mul_f32 v[0:1], v[0:1], v[132:133] op_sel_hi:[1,0]
	v_pk_mul_f32 v[4:5], v[4:5], v[12:13]
	v_add_u32_e32 v12, 0xb0, v128
	v_pk_mul_f32 v[4:5], v[0:1], v[4:5]
	v_pk_mul_f32 v[0:1], v[2:3], v[132:133] op_sel_hi:[1,0]
	v_pk_mul_f32 v[2:3], v[6:7], v[14:15]
	s_nop 0
	v_pk_mul_f32 v[6:7], v[0:1], v[2:3]
	v_cvt_pk_bf16_f32 v0, v8, v9
	v_cvt_pk_bf16_f32 v1, v10, v11
	v_cvt_pk_bf16_f32 v2, v4, v5
	v_cvt_pk_bf16_f32 v3, v6, v7
	v_mad_i64_i32 v[4:5], s[14:15], v12, s75, v[130:131]
	global_store_dwordx4 v[4:5], v[0:3], off
	s_andn2_b64 vcc, exec, s[4:5]
	s_mov_b64 s[4:5], -1
	s_cbranch_vccnz .LBB0_1409
	s_branch .LBB0_1425

.LBB0_1978:
	v_lshl_add_u32 v144, s22, 8, v149
	v_ashrrev_i32_e32 v145, 31, v144
	v_lshl_add_u64 v[146:147], v[144:145], 2, s[8:9]
	global_load_dword v145, v[146:147], off
	global_load_dword v148, v[146:147], off offset:64
	global_load_dword v150, v[146:147], off offset:128
	global_load_dword v152, v[146:147], off offset:192
	global_load_dword v154, v[146:147], off offset:512
	global_load_dword v156, v[146:147], off offset:576
	global_load_dword v162, v[146:147], off offset:640
	global_load_dword v163, v[146:147], off offset:704
	v_lshl_or_b32 v146, s46, 7, v153
	v_ashrrev_i32_e32 v147, 31, v146
	v_lshl_add_u64 v[146:147], v[146:147], 1, s[68:69]
	v_mad_i64_i32 v[160:161], s[24:25], v144, s45, v[146:147]
	s_andn2_b64 vcc, exec, s[4:5]
	s_mov_b64 s[4:5], -1
	s_waitcnt vmcnt(0)
	v_fmamk_f32 v145, v145, 0x3a800000, v159
	v_fmamk_f32 v148, v148, 0x3a800000, v159
	v_rsq_f32_e32 v164, v148
	v_fmamk_f32 v150, v150, 0x3a800000, v159
	v_fmamk_f32 v152, v152, 0x3a800000, v159
	v_fmamk_f32 v165, v156, 0x3a800000, v159
	v_fmamk_f32 v167, v162, 0x3a800000, v159
	v_rsq_f32_e32 v162, v145
	v_fmamk_f32 v163, v163, 0x3a800000, v159
	v_rsq_f32_e32 v166, v150
	v_rsq_f32_e32 v156, v152
	v_pk_mul_f32 v[124:125], v[124:125], v[162:163] op_sel_hi:[1,0]
	v_pk_mul_f32 v[126:127], v[126:127], v[162:163] op_sel_hi:[1,0]
	v_pk_mul_f32 v[120:121], v[120:121], v[162:163] op_sel_hi:[1,0]
	v_pk_mul_f32 v[122:123], v[122:123], v[162:163] op_sel_hi:[1,0]
	v_rsq_f32_e32 v152, v165
	v_rsq_f32_e32 v150, v167
	v_rsq_f32_e32 v148, v163
	v_pk_mul_f32 v[112:113], v[112:113], v[162:163] op_sel_hi:[1,0]
	v_pk_mul_f32 v[114:115], v[114:115], v[162:163] op_sel_hi:[1,0]
	v_pk_mul_f32 v[108:109], v[108:109], v[162:163] op_sel_hi:[1,0]
	v_pk_mul_f32 v[110:111], v[110:111], v[162:163] op_sel_hi:[1,0]
	v_pk_mul_f32 v[116:117], v[116:117], v[164:165] op_sel_hi:[1,0]
	v_pk_mul_f32 v[100:101], v[100:101], v[164:165] op_sel_hi:[1,0]
	v_pk_mul_f32 v[118:119], v[118:119], v[164:165] op_sel_hi:[1,0]
	v_mul_f32_e32 v145, 0xbfb8aa3b, v124
	v_mul_f32_e32 v162, 0xbfb8aa3b, v125
	v_mul_f32_e32 v163, 0xbfb8aa3b, v126
	v_mul_f32_e32 v165, 0xbfb8aa3b, v127
	v_mul_f32_e32 v167, 0xbfb8aa3b, v120
	v_mul_f32_e32 v168, 0xbfb8aa3b, v121
	v_mul_f32_e32 v169, 0xbfb8aa3b, v122
	v_mul_f32_e32 v170, 0xbfb8aa3b, v123
	v_mul_f32_e32 v171, 0xbfb8aa3b, v116
	v_mul_f32_e32 v172, 0xbfb8aa3b, v117
	v_mul_f32_e32 v173, 0xbfb8aa3b, v118
	v_exp_f32_e32 v145, v145
	v_exp_f32_e32 v162, v162
	v_exp_f32_e32 v163, v163
	v_exp_f32_e32 v165, v165
	v_exp_f32_e32 v167, v167
	v_exp_f32_e32 v168, v168
	v_exp_f32_e32 v169, v169
	v_exp_f32_e32 v170, v170
	v_exp_f32_e32 v171, v171
	v_exp_f32_e32 v172, v172
	v_exp_f32_e32 v173, v173
	v_add_f32_e32 v145, 1.0, v145
	v_add_f32_e32 v175, 1.0, v162
	v_add_f32_e32 v176, 1.0, v163
	v_add_f32_e32 v165, 1.0, v165
	v_add_f32_e32 v167, 1.0, v167
	v_add_f32_e32 v177, 1.0, v168
	v_add_f32_e32 v178, 1.0, v169
	v_add_f32_e32 v179, 1.0, v170
	v_mul_f32_e32 v174, 0xbfb8aa3b, v119
	v_add_f32_e32 v180, 1.0, v171
	v_add_f32_e32 v181, 1.0, v172
	v_add_f32_e32 v182, 1.0, v173
	v_rcp_f32_e32 v162, v145
	v_rcp_f32_e32 v163, v175
	v_rcp_f32_e32 v168, v176
	v_rcp_f32_e32 v169, v165
	v_rcp_f32_e32 v170, v167
	v_rcp_f32_e32 v171, v177
	v_rcp_f32_e32 v172, v178
	v_rcp_f32_e32 v173, v179
	v_exp_f32_e32 v174, v174
	v_pk_mul_f32 v[124:125], v[124:125], v[162:163]
	v_pk_mul_f32 v[126:127], v[126:127], v[168:169]
	v_pk_mul_f32 v[120:121], v[120:121], v[170:171]
	v_pk_mul_f32 v[122:123], v[122:123], v[172:173]
	v_add_f32_e32 v183, 1.0, v174
	v_rcp_f32_e32 v174, v180
	v_rcp_f32_e32 v175, v181
	v_pk_mul_f32 v[112:113], v[112:113], v[124:125]
	v_pk_mul_f32 v[114:115], v[114:115], v[126:127]
	v_pk_mul_f32 v[120:121], v[108:109], v[120:121]
	v_pk_mul_f32 v[122:123], v[110:111], v[122:123]
	v_rcp_f32_e32 v176, v182
	v_cvt_pk_bf16_f32 v108, v112, v113
	v_cvt_pk_bf16_f32 v109, v114, v115
	v_cvt_pk_bf16_f32 v110, v120, v121
	v_cvt_pk_bf16_f32 v111, v122, v123
	v_rcp_f32_e32 v177, v183
	v_pk_mul_f32 v[104:105], v[104:105], v[164:165] op_sel_hi:[1,0]
	global_store_dwordx4 v[160:161], v[108:111], off
	v_pk_mul_f32 v[102:103], v[102:103], v[164:165] op_sel_hi:[1,0]
	v_pk_mul_f32 v[106:107], v[106:107], v[164:165] op_sel_hi:[1,0]
	v_mul_f32_e32 v110, 0xbfb8aa3b, v104
	v_exp_f32_e32 v110, v110
	v_pk_mul_f32 v[108:109], v[116:117], v[174:175]
	v_mul_f32_e32 v111, 0xbfb8aa3b, v107
	v_pk_mul_f32 v[100:101], v[100:101], v[108:109]
	v_pk_mul_f32 v[108:109], v[118:119], v[176:177]
	v_exp_f32_e32 v111, v111
	v_pk_mul_f32 v[102:103], v[102:103], v[108:109]
	v_mul_f32_e32 v108, 0xbfb8aa3b, v105
	v_exp_f32_e32 v109, v108
	v_add_f32_e32 v108, 1.0, v110
	v_mul_f32_e32 v110, 0xbfb8aa3b, v106
	v_exp_f32_e32 v110, v110
	v_add_f32_e32 v109, 1.0, v109
	v_rcp_f32_e32 v108, v108
	v_rcp_f32_e32 v109, v109
	v_add_f32_e32 v110, 1.0, v110
	v_add_f32_e32 v111, 1.0, v111
	v_rcp_f32_e32 v110, v110
	v_rcp_f32_e32 v111, v111
	v_pk_mul_f32 v[96:97], v[96:97], v[164:165] op_sel_hi:[1,0]
	v_pk_mul_f32 v[104:105], v[104:105], v[108:109]
	v_or_b32_e32 v108, 16, v144
	v_pk_mul_f32 v[104:105], v[96:97], v[104:105]
	v_pk_mul_f32 v[96:97], v[98:99], v[164:165] op_sel_hi:[1,0]
	v_pk_mul_f32 v[98:99], v[106:107], v[110:111]
	v_pk_mul_f32 v[92:93], v[92:93], v[166:167] op_sel_hi:[1,0]
	v_pk_mul_f32 v[106:107], v[96:97], v[98:99]
	v_cvt_pk_bf16_f32 v96, v100, v101
	v_cvt_pk_bf16_f32 v97, v102, v103
	v_cvt_pk_bf16_f32 v98, v104, v105
	v_cvt_pk_bf16_f32 v99, v106, v107
	v_mad_i64_i32 v[100:101], s[24:25], v108, s45, v[146:147]
	v_mul_f32_e32 v102, 0xbfb8aa3b, v92
	global_store_dwordx4 v[100:101], v[96:99], off
	v_pk_mul_f32 v[94:95], v[94:95], v[166:167] op_sel_hi:[1,0]
	v_exp_f32_e32 v102, v102
	v_mul_f32_e32 v96, 0xbfb8aa3b, v93
	v_exp_f32_e32 v97, v96
	v_mul_f32_e32 v98, 0xbfb8aa3b, v94
	v_mul_f32_e32 v99, 0xbfb8aa3b, v95
	v_exp_f32_e32 v98, v98
	v_exp_f32_e32 v99, v99
	v_add_f32_e32 v96, 1.0, v102
	v_add_f32_e32 v97, 1.0, v97
	v_rcp_f32_e32 v96, v96
	v_rcp_f32_e32 v97, v97
	v_add_f32_e32 v98, 1.0, v98
	v_add_f32_e32 v99, 1.0, v99
	v_rcp_f32_e32 v98, v98
	v_rcp_f32_e32 v99, v99
	v_pk_mul_f32 v[84:85], v[84:85], v[166:167] op_sel_hi:[1,0]
	v_pk_mul_f32 v[92:93], v[92:93], v[96:97]
	v_pk_mul_f32 v[88:89], v[88:89], v[166:167] op_sel_hi:[1,0]
	v_pk_mul_f32 v[84:85], v[84:85], v[92:93]
	v_pk_mul_f32 v[92:93], v[94:95], v[98:99]
	v_mul_f32_e32 v94, 0xbfb8aa3b, v88
	v_exp_f32_e32 v94, v94
	v_pk_mul_f32 v[86:87], v[86:87], v[166:167] op_sel_hi:[1,0]
	v_pk_mul_f32 v[90:91], v[90:91], v[166:167] op_sel_hi:[1,0]
	v_pk_mul_f32 v[86:87], v[86:87], v[92:93]
	v_mul_f32_e32 v92, 0xbfb8aa3b, v89
	v_exp_f32_e32 v93, v92
	v_add_f32_e32 v92, 1.0, v94
	v_mul_f32_e32 v94, 0xbfb8aa3b, v90
	v_mul_f32_e32 v95, 0xbfb8aa3b, v91
	v_exp_f32_e32 v94, v94
	v_exp_f32_e32 v95, v95
	v_add_f32_e32 v93, 1.0, v93
	v_rcp_f32_e32 v92, v92
	v_rcp_f32_e32 v93, v93
	v_add_f32_e32 v94, 1.0, v94
	v_add_f32_e32 v95, 1.0, v95
	v_rcp_f32_e32 v94, v94
	v_rcp_f32_e32 v95, v95
	v_pk_mul_f32 v[80:81], v[80:81], v[166:167] op_sel_hi:[1,0]
	v_pk_mul_f32 v[88:89], v[88:89], v[92:93]
	v_or_b32_e32 v92, 32, v144
	v_pk_mul_f32 v[88:89], v[80:81], v[88:89]
	v_pk_mul_f32 v[80:81], v[82:83], v[166:167] op_sel_hi:[1,0]
	v_pk_mul_f32 v[82:83], v[90:91], v[94:95]
	v_pk_mul_f32 v[76:77], v[76:77], v[156:157] op_sel_hi:[1,0]
	v_pk_mul_f32 v[90:91], v[80:81], v[82:83]
	v_cvt_pk_bf16_f32 v80, v84, v85
	v_cvt_pk_bf16_f32 v81, v86, v87
	v_cvt_pk_bf16_f32 v82, v88, v89
	v_cvt_pk_bf16_f32 v83, v90, v91
	v_mad_i64_i32 v[84:85], s[24:25], v92, s45, v[146:147]
	v_mul_f32_e32 v86, 0xbfb8aa3b, v76
	global_store_dwordx4 v[84:85], v[80:83], off
	v_pk_mul_f32 v[78:79], v[78:79], v[156:157] op_sel_hi:[1,0]
	v_exp_f32_e32 v86, v86
	v_mul_f32_e32 v80, 0xbfb8aa3b, v77
	v_exp_f32_e32 v81, v80
	v_mul_f32_e32 v82, 0xbfb8aa3b, v78
	v_mul_f32_e32 v83, 0xbfb8aa3b, v79
	v_exp_f32_e32 v82, v82
	v_exp_f32_e32 v83, v83
	v_add_f32_e32 v80, 1.0, v86
	v_add_f32_e32 v81, 1.0, v81
	v_rcp_f32_e32 v80, v80
	v_rcp_f32_e32 v81, v81
	v_add_f32_e32 v82, 1.0, v82
	v_add_f32_e32 v83, 1.0, v83
	v_rcp_f32_e32 v82, v82
	v_rcp_f32_e32 v83, v83
	v_pk_mul_f32 v[68:69], v[68:69], v[156:157] op_sel_hi:[1,0]
	v_pk_mul_f32 v[76:77], v[76:77], v[80:81]
	v_pk_mul_f32 v[72:73], v[72:73], v[156:157] op_sel_hi:[1,0]
	v_pk_mul_f32 v[68:69], v[68:69], v[76:77]
	v_pk_mul_f32 v[76:77], v[78:79], v[82:83]
	v_mul_f32_e32 v78, 0xbfb8aa3b, v72
	v_exp_f32_e32 v78, v78
	v_pk_mul_f32 v[70:71], v[70:71], v[156:157] op_sel_hi:[1,0]
	v_pk_mul_f32 v[74:75], v[74:75], v[156:157] op_sel_hi:[1,0]
	v_pk_mul_f32 v[70:71], v[70:71], v[76:77]
	v_mul_f32_e32 v76, 0xbfb8aa3b, v73
	v_exp_f32_e32 v77, v76
	v_add_f32_e32 v76, 1.0, v78
	v_mul_f32_e32 v78, 0xbfb8aa3b, v74
	v_mul_f32_e32 v79, 0xbfb8aa3b, v75
	v_exp_f32_e32 v78, v78
	v_exp_f32_e32 v79, v79
	v_add_f32_e32 v77, 1.0, v77
	v_rcp_f32_e32 v76, v76
	v_rcp_f32_e32 v77, v77
	v_add_f32_e32 v78, 1.0, v78
	v_add_f32_e32 v79, 1.0, v79
	v_rcp_f32_e32 v78, v78
	v_rcp_f32_e32 v79, v79
	v_fmamk_f32 v154, v154, 0x3a800000, v159
	v_rsq_f32_e32 v154, v154
	v_pk_mul_f32 v[64:65], v[64:65], v[156:157] op_sel_hi:[1,0]
	v_pk_mul_f32 v[72:73], v[72:73], v[76:77]
	v_or_b32_e32 v76, 48, v144
	v_pk_mul_f32 v[72:73], v[64:65], v[72:73]
	v_pk_mul_f32 v[64:65], v[66:67], v[156:157] op_sel_hi:[1,0]
	v_pk_mul_f32 v[66:67], v[74:75], v[78:79]
	v_pk_mul_f32 v[60:61], v[60:61], v[154:155] op_sel_hi:[1,0]
	v_pk_mul_f32 v[74:75], v[64:65], v[66:67]
	v_cvt_pk_bf16_f32 v64, v68, v69
	v_cvt_pk_bf16_f32 v65, v70, v71
	v_cvt_pk_bf16_f32 v66, v72, v73
	v_cvt_pk_bf16_f32 v67, v74, v75
	v_mad_i64_i32 v[68:69], s[24:25], v76, s45, v[146:147]
	global_store_dwordx4 v[68:69], v[64:67], off
	v_pk_mul_f32 v[62:63], v[62:63], v[154:155] op_sel_hi:[1,0]
	v_pk_mul_f32 v[52:53], v[52:53], v[154:155] op_sel_hi:[1,0]
	v_mul_f32_e32 v64, 0xbfb8aa3b, v60
	v_mul_f32_e32 v65, 0xbfb8aa3b, v61
	v_exp_f32_e32 v64, v64
	v_exp_f32_e32 v65, v65
	v_mul_f32_e32 v66, 0xbfb8aa3b, v62
	v_mul_f32_e32 v67, 0xbfb8aa3b, v63
	v_exp_f32_e32 v66, v66
	v_exp_f32_e32 v67, v67
	v_add_f32_e32 v64, 1.0, v64
	v_add_f32_e32 v65, 1.0, v65
	v_rcp_f32_e32 v64, v64
	v_rcp_f32_e32 v65, v65
	v_add_f32_e32 v66, 1.0, v66
	v_add_f32_e32 v67, 1.0, v67
	v_rcp_f32_e32 v66, v66
	v_rcp_f32_e32 v67, v67
	v_pk_mul_f32 v[60:61], v[60:61], v[64:65]
	v_pk_mul_f32 v[56:57], v[56:57], v[154:155] op_sel_hi:[1,0]
	v_pk_mul_f32 v[52:53], v[52:53], v[60:61]
	v_pk_mul_f32 v[60:61], v[62:63], v[66:67]
	v_mul_f32_e32 v62, 0xbfb8aa3b, v56
	v_exp_f32_e32 v62, v62
	v_pk_mul_f32 v[54:55], v[54:55], v[154:155] op_sel_hi:[1,0]
	v_pk_mul_f32 v[58:59], v[58:59], v[154:155] op_sel_hi:[1,0]
	v_pk_mul_f32 v[54:55], v[54:55], v[60:61]
	v_mul_f32_e32 v60, 0xbfb8aa3b, v57
	v_exp_f32_e32 v61, v60
	v_add_f32_e32 v60, 1.0, v62
	v_mul_f32_e32 v62, 0xbfb8aa3b, v58
	v_mul_f32_e32 v63, 0xbfb8aa3b, v59
	v_exp_f32_e32 v62, v62
	v_exp_f32_e32 v63, v63
	v_add_f32_e32 v61, 1.0, v61
	v_rcp_f32_e32 v60, v60
	v_rcp_f32_e32 v61, v61
	v_add_f32_e32 v62, 1.0, v62
	v_add_f32_e32 v63, 1.0, v63
	v_rcp_f32_e32 v62, v62
	v_rcp_f32_e32 v63, v63
	v_pk_mul_f32 v[48:49], v[48:49], v[154:155] op_sel_hi:[1,0]
	v_pk_mul_f32 v[56:57], v[56:57], v[60:61]
	v_add_u32_e32 v68, 0x80, v144
	v_pk_mul_f32 v[56:57], v[48:49], v[56:57]
	v_pk_mul_f32 v[48:49], v[50:51], v[154:155] op_sel_hi:[1,0]
	v_pk_mul_f32 v[50:51], v[58:59], v[62:63]
	v_pk_mul_f32 v[44:45], v[44:45], v[152:153] op_sel_hi:[1,0]
	v_pk_mul_f32 v[58:59], v[48:49], v[50:51]
	v_cvt_pk_bf16_f32 v48, v52, v53
	v_cvt_pk_bf16_f32 v49, v54, v55
	v_cvt_pk_bf16_f32 v50, v56, v57
	v_cvt_pk_bf16_f32 v51, v58, v59
	v_mad_i64_i32 v[52:53], s[24:25], v68, s45, v[146:147]
	v_mul_f32_e32 v54, 0xbfb8aa3b, v44
	global_store_dwordx4 v[52:53], v[48:51], off
	v_pk_mul_f32 v[46:47], v[46:47], v[152:153] op_sel_hi:[1,0]
	v_exp_f32_e32 v54, v54
	v_mul_f32_e32 v48, 0xbfb8aa3b, v45
	v_exp_f32_e32 v49, v48
	v_mul_f32_e32 v50, 0xbfb8aa3b, v46
	v_mul_f32_e32 v51, 0xbfb8aa3b, v47
	v_exp_f32_e32 v50, v50
	v_exp_f32_e32 v51, v51
	v_add_f32_e32 v48, 1.0, v54
	v_add_f32_e32 v49, 1.0, v49
	v_rcp_f32_e32 v48, v48
	v_rcp_f32_e32 v49, v49
	v_add_f32_e32 v50, 1.0, v50
	v_add_f32_e32 v51, 1.0, v51
	v_rcp_f32_e32 v50, v50
	v_rcp_f32_e32 v51, v51
	v_pk_mul_f32 v[36:37], v[36:37], v[152:153] op_sel_hi:[1,0]
	v_pk_mul_f32 v[44:45], v[44:45], v[48:49]
	v_pk_mul_f32 v[40:41], v[40:41], v[152:153] op_sel_hi:[1,0]
	v_pk_mul_f32 v[36:37], v[36:37], v[44:45]
	v_pk_mul_f32 v[44:45], v[46:47], v[50:51]
	v_mul_f32_e32 v46, 0xbfb8aa3b, v40
	v_exp_f32_e32 v46, v46
	v_pk_mul_f32 v[38:39], v[38:39], v[152:153] op_sel_hi:[1,0]
	v_pk_mul_f32 v[42:43], v[42:43], v[152:153] op_sel_hi:[1,0]
	v_pk_mul_f32 v[38:39], v[38:39], v[44:45]
	v_mul_f32_e32 v44, 0xbfb8aa3b, v41
	v_exp_f32_e32 v45, v44
	v_add_f32_e32 v44, 1.0, v46
	v_mul_f32_e32 v46, 0xbfb8aa3b, v42
	v_mul_f32_e32 v47, 0xbfb8aa3b, v43
	v_exp_f32_e32 v46, v46
	v_exp_f32_e32 v47, v47
	v_add_f32_e32 v45, 1.0, v45
	v_rcp_f32_e32 v44, v44
	v_rcp_f32_e32 v45, v45
	v_add_f32_e32 v46, 1.0, v46
	v_add_f32_e32 v47, 1.0, v47
	v_rcp_f32_e32 v46, v46
	v_rcp_f32_e32 v47, v47
	v_pk_mul_f32 v[32:33], v[32:33], v[152:153] op_sel_hi:[1,0]
	v_pk_mul_f32 v[40:41], v[40:41], v[44:45]
	v_add_u32_e32 v44, 0x90, v144
	v_pk_mul_f32 v[40:41], v[32:33], v[40:41]
	v_pk_mul_f32 v[32:33], v[34:35], v[152:153] op_sel_hi:[1,0]
	v_pk_mul_f32 v[34:35], v[42:43], v[46:47]
	v_pk_mul_f32 v[28:29], v[28:29], v[150:151] op_sel_hi:[1,0]
	v_pk_mul_f32 v[42:43], v[32:33], v[34:35]
	v_cvt_pk_bf16_f32 v32, v36, v37
	v_cvt_pk_bf16_f32 v33, v38, v39
	v_cvt_pk_bf16_f32 v34, v40, v41
	v_cvt_pk_bf16_f32 v35, v42, v43
	v_mad_i64_i32 v[36:37], s[24:25], v44, s45, v[146:147]
	v_mul_f32_e32 v38, 0xbfb8aa3b, v28
	global_store_dwordx4 v[36:37], v[32:35], off
	v_pk_mul_f32 v[30:31], v[30:31], v[150:151] op_sel_hi:[1,0]
	v_exp_f32_e32 v38, v38
	v_mul_f32_e32 v32, 0xbfb8aa3b, v29
	v_exp_f32_e32 v33, v32
	v_mul_f32_e32 v34, 0xbfb8aa3b, v30
	v_mul_f32_e32 v35, 0xbfb8aa3b, v31
	v_exp_f32_e32 v34, v34
	v_exp_f32_e32 v35, v35
	v_add_f32_e32 v32, 1.0, v38
	v_add_f32_e32 v33, 1.0, v33
	v_rcp_f32_e32 v32, v32
	v_rcp_f32_e32 v33, v33
	v_add_f32_e32 v34, 1.0, v34
	v_add_f32_e32 v35, 1.0, v35
	v_rcp_f32_e32 v34, v34
	v_rcp_f32_e32 v35, v35
	v_pk_mul_f32 v[20:21], v[20:21], v[150:151] op_sel_hi:[1,0]
	v_pk_mul_f32 v[28:29], v[28:29], v[32:33]
	v_pk_mul_f32 v[24:25], v[24:25], v[150:151] op_sel_hi:[1,0]
	v_pk_mul_f32 v[20:21], v[20:21], v[28:29]
	v_pk_mul_f32 v[28:29], v[30:31], v[34:35]
	v_mul_f32_e32 v30, 0xbfb8aa3b, v24
	v_exp_f32_e32 v30, v30
	v_pk_mul_f32 v[22:23], v[22:23], v[150:151] op_sel_hi:[1,0]
	v_pk_mul_f32 v[26:27], v[26:27], v[150:151] op_sel_hi:[1,0]
	v_pk_mul_f32 v[22:23], v[22:23], v[28:29]
	v_mul_f32_e32 v28, 0xbfb8aa3b, v25
	v_exp_f32_e32 v29, v28
	v_add_f32_e32 v28, 1.0, v30
	v_mul_f32_e32 v30, 0xbfb8aa3b, v26
	v_mul_f32_e32 v31, 0xbfb8aa3b, v27
	v_exp_f32_e32 v30, v30
	v_exp_f32_e32 v31, v31
	v_add_f32_e32 v29, 1.0, v29
	v_rcp_f32_e32 v28, v28
	v_rcp_f32_e32 v29, v29
	v_add_f32_e32 v30, 1.0, v30
	v_add_f32_e32 v31, 1.0, v31
	v_rcp_f32_e32 v30, v30
	v_rcp_f32_e32 v31, v31
	v_pk_mul_f32 v[16:17], v[16:17], v[150:151] op_sel_hi:[1,0]
	v_pk_mul_f32 v[24:25], v[24:25], v[28:29]
	v_add_u32_e32 v28, 0xa0, v144
	v_pk_mul_f32 v[24:25], v[16:17], v[24:25]
	v_pk_mul_f32 v[16:17], v[18:19], v[150:151] op_sel_hi:[1,0]
	v_pk_mul_f32 v[18:19], v[26:27], v[30:31]
	v_pk_mul_f32 v[12:13], v[12:13], v[148:149] op_sel_hi:[1,0]
	v_pk_mul_f32 v[26:27], v[16:17], v[18:19]
	v_cvt_pk_bf16_f32 v16, v20, v21
	v_cvt_pk_bf16_f32 v17, v22, v23
	v_cvt_pk_bf16_f32 v18, v24, v25
	v_cvt_pk_bf16_f32 v19, v26, v27
	v_mad_i64_i32 v[20:21], s[24:25], v28, s45, v[146:147]
	v_mul_f32_e32 v22, 0xbfb8aa3b, v12
	global_store_dwordx4 v[20:21], v[16:19], off
	v_pk_mul_f32 v[14:15], v[14:15], v[148:149] op_sel_hi:[1,0]
	v_exp_f32_e32 v22, v22
	v_mul_f32_e32 v16, 0xbfb8aa3b, v13
	v_exp_f32_e32 v17, v16
	v_mul_f32_e32 v18, 0xbfb8aa3b, v14
	v_mul_f32_e32 v19, 0xbfb8aa3b, v15
	v_exp_f32_e32 v18, v18
	v_exp_f32_e32 v19, v19
	v_add_f32_e32 v16, 1.0, v22
	v_add_f32_e32 v17, 1.0, v17
	v_rcp_f32_e32 v16, v16
	v_rcp_f32_e32 v17, v17
	v_add_f32_e32 v18, 1.0, v18
	v_add_f32_e32 v19, 1.0, v19
	v_rcp_f32_e32 v18, v18
	v_rcp_f32_e32 v19, v19
	v_pk_mul_f32 v[4:5], v[4:5], v[148:149] op_sel_hi:[1,0]
	v_pk_mul_f32 v[12:13], v[12:13], v[16:17]
	v_pk_mul_f32 v[8:9], v[8:9], v[148:149] op_sel_hi:[1,0]
	v_pk_mul_f32 v[4:5], v[4:5], v[12:13]
	v_pk_mul_f32 v[12:13], v[14:15], v[18:19]
	v_mul_f32_e32 v14, 0xbfb8aa3b, v8
	v_exp_f32_e32 v14, v14
	v_pk_mul_f32 v[6:7], v[6:7], v[148:149] op_sel_hi:[1,0]
	v_pk_mul_f32 v[10:11], v[10:11], v[148:149] op_sel_hi:[1,0]
	v_pk_mul_f32 v[6:7], v[6:7], v[12:13]
	v_mul_f32_e32 v12, 0xbfb8aa3b, v9
	v_exp_f32_e32 v13, v12
	v_add_f32_e32 v12, 1.0, v14
	v_mul_f32_e32 v14, 0xbfb8aa3b, v10
	v_mul_f32_e32 v15, 0xbfb8aa3b, v11
	v_exp_f32_e32 v14, v14
	v_exp_f32_e32 v15, v15
	v_add_f32_e32 v13, 1.0, v13
	v_rcp_f32_e32 v12, v12
	v_rcp_f32_e32 v13, v13
	v_add_f32_e32 v14, 1.0, v14
	v_add_f32_e32 v15, 1.0, v15
	v_rcp_f32_e32 v14, v14
	v_rcp_f32_e32 v15, v15
	v_pk_mul_f32 v[0:1], v[0:1], v[148:149] op_sel_hi:[1,0]
	v_pk_mul_f32 v[8:9], v[8:9], v[12:13]
	v_add_u32_e32 v12, 0xb0, v144
	v_pk_mul_f32 v[8:9], v[0:1], v[8:9]
	v_pk_mul_f32 v[0:1], v[2:3], v[148:149] op_sel_hi:[1,0]
	v_pk_mul_f32 v[2:3], v[10:11], v[14:15]
	s_nop 0
	v_pk_mul_f32 v[10:11], v[0:1], v[2:3]
	v_cvt_pk_bf16_f32 v0, v4, v5
	v_cvt_pk_bf16_f32 v1, v6, v7
	v_cvt_pk_bf16_f32 v2, v8, v9
	v_cvt_pk_bf16_f32 v3, v10, v11
	v_mad_i64_i32 v[4:5], s[24:25], v12, s45, v[146:147]
	global_store_dwordx4 v[4:5], v[0:3], off
	s_cbranch_vccnz .LBB0_1971
	s_andn2_b64 vcc, exec, s[6:7]
	s_cbranch_vccnz .LBB0_1970
	s_barrier
	s_branch .LBB0_1970
